# v5 (aligned) plus EpiRes (P5/P9) residual-row loads kept 6 deep in flight through a VGPR ring instead of one exposed load per row group
# speedup vs baseline: 1.0079x; 1.0075x over previous
.LBB0_1080:
	v_lshl_add_u32 v148, s42, 8, v151
	v_lshl_or_b32 v146, s35, 8, v153
	v_ashrrev_i32_e32 v149, 31, v148
	v_ashrrev_i32_e32 v147, 31, v146
	v_lshlrev_b64 v[144:145], 10, v[148:149]
	v_lshl_add_u64 v[144:145], v[144:145], 0, v[146:147]
	v_lshlrev_b64 v[144:145], 1, v[144:145]
	v_lshl_add_u64 v[162:163], s[14:15], 0, v[144:145]
	v_mov_b64_e32 v[252:253], v[162:163]
	global_load_dwordx4 v[226:229], v[252:253], off
	global_load_dwordx4 v[230:233], v[252:253], off offset:256
	s_mov_b64 s[98:99], 0x8000
	v_lshl_add_u64 v[250:251], v[252:253], 0, s[98:99]
	global_load_dwordx4 v[234:237], v[250:251], off
	global_load_dwordx4 v[238:241], v[250:251], off offset:256
	s_mov_b64 s[98:99], 0x10000
	v_lshl_add_u64 v[250:251], v[252:253], 0, s[98:99]
	global_load_dwordx4 v[242:245], v[250:251], off
	global_load_dwordx4 v[246:249], v[250:251], off offset:256
	s_andn2_b64 vcc, exec, s[6:7]
	s_mov_b64 s[6:7], -1
	s_waitcnt vmcnt(5)
	s_nop 1
	v_mov_b32_e32 v158, v226
	v_mov_b32_e32 v159, v227
	v_mov_b32_e32 v160, v228
	v_mov_b32_e32 v161, v229
	s_mov_b64 s[98:99], 0x18000
	v_lshl_add_u64 v[250:251], v[252:253], 0, s[98:99]
	global_load_dwordx4 v[226:229], v[250:251], off
	v_lshlrev_b32_e32 v149, 16, v158
	v_and_b32_e32 v157, 0xffff0000, v158
	v_lshlrev_b32_e32 v158, 16, v159
	v_and_b32_e32 v159, 0xffff0000, v159
	v_lshlrev_b32_e32 v165, 16, v161
	v_and_b32_e32 v161, 0xffff0000, v161
	v_lshlrev_b32_e32 v164, 16, v160
	v_and_b32_e32 v160, 0xffff0000, v160
	v_fmamk_f32 v124, v149, 0x3f9837f0, v124
	v_fmamk_f32 v125, v157, 0x3f9837f0, v125
	v_fmamk_f32 v126, v158, 0x3f9837f0, v126
	v_fmac_f32_e32 v127, 0x3f9837f0, v159
	v_fmac_f32_e32 v123, 0x3f9837f0, v161
	v_fmamk_f32 v149, v164, 0x3f9837f0, v120
	v_fmamk_f32 v157, v160, 0x3f9837f0, v121
	v_fmamk_f32 v158, v165, 0x3f9837f0, v122
	v_cvt_pk_bf16_f32 v120, v124, v125
	v_cvt_pk_bf16_f32 v121, v126, v127
	v_cvt_pk_bf16_f32 v122, v149, v157
	v_cvt_pk_bf16_f32 v123, v158, v123
	v_or_b32_e32 v158, 16, v148
	v_ashrrev_i32_e32 v159, 31, v158
	v_lshlrev_b64 v[158:159], 10, v[158:159]
	v_lshl_add_u64 v[160:161], s[12:13], 0, v[144:145]
	v_lshl_add_u64 v[158:159], v[158:159], 0, v[146:147]
	global_store_dwordx4 v[160:161], v[120:123], off
	v_lshlrev_b64 v[158:159], 1, v[158:159]
	v_lshl_add_u64 v[162:163], s[14:15], 0, v[158:159]
	s_waitcnt vmcnt(6)
	s_nop 1
	v_mov_b32_e32 v124, v230
	v_mov_b32_e32 v125, v231
	v_mov_b32_e32 v126, v232
	v_mov_b32_e32 v127, v233
	global_load_dwordx4 v[230:233], v[250:251], off offset:256
	v_lshlrev_b32_e32 v120, 16, v124
	v_and_b32_e32 v121, 0xffff0000, v124
	v_lshlrev_b32_e32 v122, 16, v125
	v_and_b32_e32 v123, 0xffff0000, v125
	v_lshlrev_b32_e32 v124, 16, v126
	v_and_b32_e32 v125, 0xffff0000, v126
	v_lshlrev_b32_e32 v126, 16, v127
	v_and_b32_e32 v127, 0xffff0000, v127
	v_fmac_f32_e32 v115, 0x3f9837f0, v127
	v_fmamk_f32 v116, v120, 0x3f9837f0, v116
	v_fmamk_f32 v117, v121, 0x3f9837f0, v117
	v_fmamk_f32 v118, v122, 0x3f9837f0, v118
	v_fmac_f32_e32 v119, 0x3f9837f0, v123
	v_fmamk_f32 v120, v124, 0x3f9837f0, v112
	v_fmamk_f32 v121, v125, 0x3f9837f0, v113
	v_fmamk_f32 v122, v126, 0x3f9837f0, v114
	v_cvt_pk_bf16_f32 v112, v116, v117
	v_cvt_pk_bf16_f32 v113, v118, v119
	v_cvt_pk_bf16_f32 v114, v120, v121
	v_cvt_pk_bf16_f32 v115, v122, v115
	global_store_dwordx4 v[160:161], v[112:115], off offset:256
	s_waitcnt vmcnt(7)
	s_nop 1
	v_mov_b32_e32 v112, v234
	v_mov_b32_e32 v113, v235
	v_mov_b32_e32 v114, v236
	v_mov_b32_e32 v115, v237
	s_mov_b64 s[98:99], 0x40000
	v_lshl_add_u64 v[250:251], v[252:253], 0, s[98:99]
	global_load_dwordx4 v[234:237], v[250:251], off
	v_lshlrev_b32_e32 v116, 16, v112
	v_and_b32_e32 v112, 0xffff0000, v112
	v_lshlrev_b32_e32 v117, 16, v113
	v_and_b32_e32 v113, 0xffff0000, v113
	v_lshlrev_b32_e32 v119, 16, v115
	v_and_b32_e32 v115, 0xffff0000, v115
	v_lshlrev_b32_e32 v118, 16, v114
	v_and_b32_e32 v114, 0xffff0000, v114
	v_fmamk_f32 v108, v116, 0x3f9837f0, v108
	v_fmamk_f32 v109, v112, 0x3f9837f0, v109
	v_fmamk_f32 v110, v117, 0x3f9837f0, v110
	v_fmac_f32_e32 v111, 0x3f9837f0, v113
	v_fmac_f32_e32 v107, 0x3f9837f0, v115
	v_fmamk_f32 v112, v118, 0x3f9837f0, v104
	v_fmamk_f32 v113, v114, 0x3f9837f0, v105
	v_fmamk_f32 v114, v119, 0x3f9837f0, v106
	v_cvt_pk_bf16_f32 v104, v108, v109
	v_cvt_pk_bf16_f32 v105, v110, v111
	v_cvt_pk_bf16_f32 v106, v112, v113
	v_cvt_pk_bf16_f32 v107, v114, v107
	v_or_b32_e32 v112, 32, v148
	v_ashrrev_i32_e32 v113, 31, v112
	v_lshlrev_b64 v[112:113], 10, v[112:113]
	v_lshl_add_u64 v[114:115], s[12:13], 0, v[158:159]
	v_lshl_add_u64 v[112:113], v[112:113], 0, v[146:147]
	global_store_dwordx4 v[114:115], v[104:107], off
	v_lshlrev_b64 v[112:113], 1, v[112:113]
	v_lshl_add_u64 v[116:117], s[14:15], 0, v[112:113]
	s_waitcnt vmcnt(8)
	s_nop 1
	v_mov_b32_e32 v108, v238
	v_mov_b32_e32 v109, v239
	v_mov_b32_e32 v110, v240
	v_mov_b32_e32 v111, v241
	global_load_dwordx4 v[238:241], v[250:251], off offset:256
	v_lshlrev_b32_e32 v104, 16, v108
	v_and_b32_e32 v105, 0xffff0000, v108
	v_lshlrev_b32_e32 v106, 16, v109
	v_and_b32_e32 v107, 0xffff0000, v109
	v_lshlrev_b32_e32 v108, 16, v110
	v_and_b32_e32 v109, 0xffff0000, v110
	v_lshlrev_b32_e32 v110, 16, v111
	v_and_b32_e32 v111, 0xffff0000, v111
	v_fmac_f32_e32 v99, 0x3f9837f0, v111
	v_fmamk_f32 v100, v104, 0x3f9837f0, v100
	v_fmamk_f32 v101, v105, 0x3f9837f0, v101
	v_fmamk_f32 v102, v106, 0x3f9837f0, v102
	v_fmac_f32_e32 v103, 0x3f9837f0, v107
	v_fmamk_f32 v104, v108, 0x3f9837f0, v96
	v_fmamk_f32 v105, v109, 0x3f9837f0, v97
	v_fmamk_f32 v106, v110, 0x3f9837f0, v98
	v_cvt_pk_bf16_f32 v96, v100, v101
	v_cvt_pk_bf16_f32 v97, v102, v103
	v_cvt_pk_bf16_f32 v98, v104, v105
	v_cvt_pk_bf16_f32 v99, v106, v99
	global_store_dwordx4 v[114:115], v[96:99], off offset:256
	s_waitcnt vmcnt(9)
	s_nop 1
	v_mov_b32_e32 v96, v242
	v_mov_b32_e32 v97, v243
	v_mov_b32_e32 v98, v244
	v_mov_b32_e32 v99, v245
	s_mov_b64 s[98:99], 0x48000
	v_lshl_add_u64 v[250:251], v[252:253], 0, s[98:99]
	global_load_dwordx4 v[242:245], v[250:251], off
	v_lshlrev_b32_e32 v100, 16, v96
	v_and_b32_e32 v96, 0xffff0000, v96
	v_lshlrev_b32_e32 v101, 16, v97
	v_and_b32_e32 v97, 0xffff0000, v97
	v_lshlrev_b32_e32 v103, 16, v99
	v_and_b32_e32 v99, 0xffff0000, v99
	v_lshlrev_b32_e32 v102, 16, v98
	v_and_b32_e32 v98, 0xffff0000, v98
	v_fmamk_f32 v92, v100, 0x3f9837f0, v92
	v_fmamk_f32 v93, v96, 0x3f9837f0, v93
	v_fmamk_f32 v94, v101, 0x3f9837f0, v94
	v_fmac_f32_e32 v95, 0x3f9837f0, v97
	v_fmac_f32_e32 v91, 0x3f9837f0, v99
	v_fmamk_f32 v96, v102, 0x3f9837f0, v88
	v_fmamk_f32 v97, v98, 0x3f9837f0, v89
	v_fmamk_f32 v98, v103, 0x3f9837f0, v90
	v_cvt_pk_bf16_f32 v88, v92, v93
	v_cvt_pk_bf16_f32 v89, v94, v95
	v_cvt_pk_bf16_f32 v90, v96, v97
	v_cvt_pk_bf16_f32 v91, v98, v91
	v_or_b32_e32 v96, 48, v148
	v_ashrrev_i32_e32 v97, 31, v96
	v_lshlrev_b64 v[96:97], 10, v[96:97]
	v_lshl_add_u64 v[98:99], s[12:13], 0, v[112:113]
	v_lshl_add_u64 v[96:97], v[96:97], 0, v[146:147]
	global_store_dwordx4 v[98:99], v[88:91], off
	v_lshlrev_b64 v[96:97], 1, v[96:97]
	v_lshl_add_u64 v[100:101], s[14:15], 0, v[96:97]
	s_waitcnt vmcnt(10)
	s_nop 1
	v_mov_b32_e32 v92, v246
	v_mov_b32_e32 v93, v247
	v_mov_b32_e32 v94, v248
	v_mov_b32_e32 v95, v249
	global_load_dwordx4 v[246:249], v[250:251], off offset:256
	v_lshlrev_b32_e32 v88, 16, v92
	v_and_b32_e32 v89, 0xffff0000, v92
	v_lshlrev_b32_e32 v90, 16, v93
	v_and_b32_e32 v91, 0xffff0000, v93
	v_lshlrev_b32_e32 v92, 16, v94
	v_and_b32_e32 v93, 0xffff0000, v94
	v_lshlrev_b32_e32 v94, 16, v95
	v_and_b32_e32 v95, 0xffff0000, v95
	v_fmac_f32_e32 v83, 0x3f9837f0, v95
	v_fmamk_f32 v84, v88, 0x3f9837f0, v84
	v_fmamk_f32 v85, v89, 0x3f9837f0, v85
	v_fmamk_f32 v86, v90, 0x3f9837f0, v86
	v_fmac_f32_e32 v87, 0x3f9837f0, v91
	v_fmamk_f32 v88, v92, 0x3f9837f0, v80
	v_fmamk_f32 v89, v93, 0x3f9837f0, v81
	v_fmamk_f32 v90, v94, 0x3f9837f0, v82
	v_cvt_pk_bf16_f32 v80, v84, v85
	v_cvt_pk_bf16_f32 v81, v86, v87
	v_cvt_pk_bf16_f32 v82, v88, v89
	v_cvt_pk_bf16_f32 v83, v90, v83
	global_store_dwordx4 v[98:99], v[80:83], off offset:256
	s_waitcnt vmcnt(11)
	s_nop 1
	v_mov_b32_e32 v80, v226
	v_mov_b32_e32 v81, v227
	v_mov_b32_e32 v82, v228
	v_mov_b32_e32 v83, v229
	s_mov_b64 s[98:99], 0x50000
	v_lshl_add_u64 v[250:251], v[252:253], 0, s[98:99]
	global_load_dwordx4 v[226:229], v[250:251], off
	v_lshlrev_b32_e32 v84, 16, v80
	v_and_b32_e32 v80, 0xffff0000, v80
	v_lshlrev_b32_e32 v85, 16, v81
	v_and_b32_e32 v81, 0xffff0000, v81
	v_lshlrev_b32_e32 v87, 16, v83
	v_and_b32_e32 v83, 0xffff0000, v83
	v_lshlrev_b32_e32 v86, 16, v82
	v_and_b32_e32 v82, 0xffff0000, v82
	v_fmamk_f32 v76, v84, 0x3f9837f0, v76
	v_fmamk_f32 v77, v80, 0x3f9837f0, v77
	v_fmamk_f32 v78, v85, 0x3f9837f0, v78
	v_fmac_f32_e32 v79, 0x3f9837f0, v81
	v_fmac_f32_e32 v75, 0x3f9837f0, v83
	v_fmamk_f32 v80, v86, 0x3f9837f0, v72
	v_fmamk_f32 v81, v82, 0x3f9837f0, v73
	v_fmamk_f32 v82, v87, 0x3f9837f0, v74
	v_cvt_pk_bf16_f32 v72, v76, v77
	v_cvt_pk_bf16_f32 v73, v78, v79
	v_cvt_pk_bf16_f32 v74, v80, v81
	v_cvt_pk_bf16_f32 v75, v82, v75
	v_lshl_add_u64 v[82:83], s[12:13], 0, v[96:97]
	global_store_dwordx4 v[82:83], v[72:75], off
	v_lshl_add_u64 v[80:81], v[144:145], 0, s[8:9]
	v_lshl_add_u64 v[84:85], s[14:15], 0, v[80:81]
	s_waitcnt vmcnt(11)
	s_nop 1
	v_mov_b32_e32 v76, v230
	v_mov_b32_e32 v77, v231
	v_mov_b32_e32 v78, v232
	v_mov_b32_e32 v79, v233
	global_load_dwordx4 v[230:233], v[250:251], off offset:256
	v_lshlrev_b32_e32 v72, 16, v76
	v_and_b32_e32 v73, 0xffff0000, v76
	v_lshlrev_b32_e32 v74, 16, v77
	v_and_b32_e32 v75, 0xffff0000, v77
	v_lshlrev_b32_e32 v76, 16, v78
	v_and_b32_e32 v77, 0xffff0000, v78
	v_lshlrev_b32_e32 v78, 16, v79
	v_and_b32_e32 v79, 0xffff0000, v79
	v_fmac_f32_e32 v67, 0x3f9837f0, v79
	v_fmamk_f32 v68, v72, 0x3f9837f0, v68
	v_fmamk_f32 v69, v73, 0x3f9837f0, v69
	v_fmamk_f32 v70, v74, 0x3f9837f0, v70
	v_fmac_f32_e32 v71, 0x3f9837f0, v75
	v_fmamk_f32 v72, v76, 0x3f9837f0, v64
	v_fmamk_f32 v73, v77, 0x3f9837f0, v65
	v_fmamk_f32 v74, v78, 0x3f9837f0, v66
	v_cvt_pk_bf16_f32 v64, v68, v69
	v_cvt_pk_bf16_f32 v65, v70, v71
	v_cvt_pk_bf16_f32 v66, v72, v73
	v_cvt_pk_bf16_f32 v67, v74, v67
	global_store_dwordx4 v[82:83], v[64:67], off offset:256
	s_waitcnt vmcnt(11)
	s_nop 1
	v_mov_b32_e32 v64, v234
	v_mov_b32_e32 v65, v235
	v_mov_b32_e32 v66, v236
	v_mov_b32_e32 v67, v237
	s_mov_b64 s[98:99], 0x58000
	v_lshl_add_u64 v[250:251], v[252:253], 0, s[98:99]
	global_load_dwordx4 v[234:237], v[250:251], off
	v_lshlrev_b32_e32 v68, 16, v64
	v_and_b32_e32 v64, 0xffff0000, v64
	v_lshlrev_b32_e32 v69, 16, v65
	v_and_b32_e32 v65, 0xffff0000, v65
	v_lshlrev_b32_e32 v71, 16, v67
	v_and_b32_e32 v67, 0xffff0000, v67
	v_lshlrev_b32_e32 v70, 16, v66
	v_and_b32_e32 v66, 0xffff0000, v66
	v_fmamk_f32 v60, v68, 0x3f9837f0, v60
	v_fmamk_f32 v61, v64, 0x3f9837f0, v61
	v_fmamk_f32 v62, v69, 0x3f9837f0, v62
	v_fmac_f32_e32 v63, 0x3f9837f0, v65
	v_fmac_f32_e32 v59, 0x3f9837f0, v67
	v_fmamk_f32 v64, v70, 0x3f9837f0, v56
	v_fmamk_f32 v65, v66, 0x3f9837f0, v57
	v_fmamk_f32 v66, v71, 0x3f9837f0, v58
	v_cvt_pk_bf16_f32 v56, v60, v61
	v_cvt_pk_bf16_f32 v57, v62, v63
	v_cvt_pk_bf16_f32 v58, v64, v65
	v_cvt_pk_bf16_f32 v59, v66, v59
	v_lshl_add_u64 v[66:67], s[12:13], 0, v[80:81]
	global_store_dwordx4 v[66:67], v[56:59], off
	v_lshl_add_u64 v[64:65], v[144:145], 0, s[20:21]
	v_lshl_add_u64 v[68:69], s[14:15], 0, v[64:65]
	s_waitcnt vmcnt(11)
	s_nop 1
	v_mov_b32_e32 v60, v238
	v_mov_b32_e32 v61, v239
	v_mov_b32_e32 v62, v240
	v_mov_b32_e32 v63, v241
	global_load_dwordx4 v[238:241], v[250:251], off offset:256
	v_lshlrev_b32_e32 v56, 16, v60
	v_and_b32_e32 v57, 0xffff0000, v60
	v_lshlrev_b32_e32 v58, 16, v61
	v_and_b32_e32 v59, 0xffff0000, v61
	v_lshlrev_b32_e32 v60, 16, v62
	v_and_b32_e32 v61, 0xffff0000, v62
	v_lshlrev_b32_e32 v62, 16, v63
	v_and_b32_e32 v63, 0xffff0000, v63
	v_fmac_f32_e32 v51, 0x3f9837f0, v63
	v_fmamk_f32 v52, v56, 0x3f9837f0, v52
	v_fmamk_f32 v53, v57, 0x3f9837f0, v53
	v_fmamk_f32 v54, v58, 0x3f9837f0, v54
	v_fmac_f32_e32 v55, 0x3f9837f0, v59
	v_fmamk_f32 v56, v60, 0x3f9837f0, v48
	v_fmamk_f32 v57, v61, 0x3f9837f0, v49
	v_fmamk_f32 v58, v62, 0x3f9837f0, v50
	v_cvt_pk_bf16_f32 v48, v52, v53
	v_cvt_pk_bf16_f32 v49, v54, v55
	v_cvt_pk_bf16_f32 v50, v56, v57
	v_cvt_pk_bf16_f32 v51, v58, v51
	global_store_dwordx4 v[66:67], v[48:51], off offset:256
	s_waitcnt vmcnt(11)
	s_nop 1
	v_mov_b32_e32 v48, v242
	v_mov_b32_e32 v49, v243
	v_mov_b32_e32 v50, v244
	v_mov_b32_e32 v51, v245
	v_lshlrev_b32_e32 v52, 16, v48
	v_and_b32_e32 v48, 0xffff0000, v48
	v_lshlrev_b32_e32 v53, 16, v49
	v_and_b32_e32 v49, 0xffff0000, v49
	v_lshlrev_b32_e32 v55, 16, v51
	v_and_b32_e32 v51, 0xffff0000, v51
	v_lshlrev_b32_e32 v54, 16, v50
	v_and_b32_e32 v50, 0xffff0000, v50
	v_fmamk_f32 v44, v52, 0x3f9837f0, v44
	v_fmamk_f32 v45, v48, 0x3f9837f0, v45
	v_fmamk_f32 v46, v53, 0x3f9837f0, v46
	v_fmac_f32_e32 v47, 0x3f9837f0, v49
	v_fmac_f32_e32 v43, 0x3f9837f0, v51
	v_fmamk_f32 v48, v54, 0x3f9837f0, v40
	v_fmamk_f32 v49, v50, 0x3f9837f0, v41
	v_fmamk_f32 v50, v55, 0x3f9837f0, v42
	v_cvt_pk_bf16_f32 v40, v44, v45
	v_cvt_pk_bf16_f32 v41, v46, v47
	v_cvt_pk_bf16_f32 v42, v48, v49
	v_cvt_pk_bf16_f32 v43, v50, v43
	v_lshl_add_u64 v[50:51], s[12:13], 0, v[64:65]
	global_store_dwordx4 v[50:51], v[40:43], off
	v_lshl_add_u64 v[48:49], v[144:145], 0, s[22:23]
	v_lshl_add_u64 v[52:53], s[14:15], 0, v[48:49]
	s_waitcnt vmcnt(10)
	s_nop 1
	v_mov_b32_e32 v44, v246
	v_mov_b32_e32 v45, v247
	v_mov_b32_e32 v46, v248
	v_mov_b32_e32 v47, v249
	v_lshlrev_b32_e32 v40, 16, v44
	v_and_b32_e32 v41, 0xffff0000, v44
	v_lshlrev_b32_e32 v42, 16, v45
	v_and_b32_e32 v43, 0xffff0000, v45
	v_lshlrev_b32_e32 v44, 16, v46
	v_and_b32_e32 v45, 0xffff0000, v46
	v_lshlrev_b32_e32 v46, 16, v47
	v_and_b32_e32 v47, 0xffff0000, v47
	v_fmac_f32_e32 v35, 0x3f9837f0, v47
	v_fmamk_f32 v36, v40, 0x3f9837f0, v36
	v_fmamk_f32 v37, v41, 0x3f9837f0, v37
	v_fmamk_f32 v38, v42, 0x3f9837f0, v38
	v_fmac_f32_e32 v39, 0x3f9837f0, v43
	v_fmamk_f32 v40, v44, 0x3f9837f0, v32
	v_fmamk_f32 v41, v45, 0x3f9837f0, v33
	v_fmamk_f32 v42, v46, 0x3f9837f0, v34
	v_cvt_pk_bf16_f32 v32, v36, v37
	v_cvt_pk_bf16_f32 v33, v38, v39
	v_cvt_pk_bf16_f32 v34, v40, v41
	v_cvt_pk_bf16_f32 v35, v42, v35
	global_store_dwordx4 v[50:51], v[32:35], off offset:256
	s_waitcnt vmcnt(9)
	s_nop 1
	v_mov_b32_e32 v32, v226
	v_mov_b32_e32 v33, v227
	v_mov_b32_e32 v34, v228
	v_mov_b32_e32 v35, v229
	v_lshlrev_b32_e32 v36, 16, v32
	v_and_b32_e32 v32, 0xffff0000, v32
	v_lshlrev_b32_e32 v37, 16, v33
	v_and_b32_e32 v33, 0xffff0000, v33
	v_lshlrev_b32_e32 v39, 16, v35
	v_and_b32_e32 v35, 0xffff0000, v35
	v_lshlrev_b32_e32 v38, 16, v34
	v_and_b32_e32 v34, 0xffff0000, v34
	v_fmamk_f32 v28, v36, 0x3f9837f0, v28
	v_fmamk_f32 v29, v32, 0x3f9837f0, v29
	v_fmamk_f32 v30, v37, 0x3f9837f0, v30
	v_fmac_f32_e32 v31, 0x3f9837f0, v33
	v_fmac_f32_e32 v27, 0x3f9837f0, v35
	v_fmamk_f32 v32, v38, 0x3f9837f0, v24
	v_fmamk_f32 v33, v34, 0x3f9837f0, v25
	v_fmamk_f32 v34, v39, 0x3f9837f0, v26
	v_cvt_pk_bf16_f32 v24, v28, v29
	v_cvt_pk_bf16_f32 v25, v30, v31
	v_cvt_pk_bf16_f32 v26, v32, v33
	v_cvt_pk_bf16_f32 v27, v34, v27
	v_lshl_add_u64 v[34:35], s[12:13], 0, v[48:49]
	global_store_dwordx4 v[34:35], v[24:27], off
	v_lshl_add_u64 v[32:33], v[144:145], 0, s[24:25]
	v_lshl_add_u64 v[36:37], s[14:15], 0, v[32:33]
	s_waitcnt vmcnt(8)
	s_nop 1
	v_mov_b32_e32 v28, v230
	v_mov_b32_e32 v29, v231
	v_mov_b32_e32 v30, v232
	v_mov_b32_e32 v31, v233
	v_lshlrev_b32_e32 v24, 16, v28
	v_and_b32_e32 v25, 0xffff0000, v28
	v_lshlrev_b32_e32 v26, 16, v29
	v_and_b32_e32 v27, 0xffff0000, v29
	v_lshlrev_b32_e32 v28, 16, v30
	v_and_b32_e32 v29, 0xffff0000, v30
	v_lshlrev_b32_e32 v30, 16, v31
	v_and_b32_e32 v31, 0xffff0000, v31
	v_fmac_f32_e32 v19, 0x3f9837f0, v31
	v_fmamk_f32 v20, v24, 0x3f9837f0, v20
	v_fmamk_f32 v21, v25, 0x3f9837f0, v21
	v_fmamk_f32 v22, v26, 0x3f9837f0, v22
	v_fmac_f32_e32 v23, 0x3f9837f0, v27
	v_fmamk_f32 v24, v28, 0x3f9837f0, v16
	v_fmamk_f32 v25, v29, 0x3f9837f0, v17
	v_fmamk_f32 v26, v30, 0x3f9837f0, v18
	v_cvt_pk_bf16_f32 v16, v20, v21
	v_cvt_pk_bf16_f32 v17, v22, v23
	v_cvt_pk_bf16_f32 v18, v24, v25
	v_cvt_pk_bf16_f32 v19, v26, v19
	global_store_dwordx4 v[34:35], v[16:19], off offset:256
	s_waitcnt vmcnt(7)
	s_nop 1
	v_mov_b32_e32 v16, v234
	v_mov_b32_e32 v17, v235
	v_mov_b32_e32 v18, v236
	v_mov_b32_e32 v19, v237
	v_lshlrev_b32_e32 v20, 16, v16
	v_and_b32_e32 v16, 0xffff0000, v16
	v_lshlrev_b32_e32 v21, 16, v17
	v_and_b32_e32 v17, 0xffff0000, v17
	v_lshlrev_b32_e32 v23, 16, v19
	v_and_b32_e32 v19, 0xffff0000, v19
	v_lshlrev_b32_e32 v22, 16, v18
	v_and_b32_e32 v18, 0xffff0000, v18
	v_fmamk_f32 v12, v20, 0x3f9837f0, v12
	v_fmamk_f32 v13, v16, 0x3f9837f0, v13
	v_fmamk_f32 v14, v21, 0x3f9837f0, v14
	v_fmac_f32_e32 v15, 0x3f9837f0, v17
	v_fmac_f32_e32 v11, 0x3f9837f0, v19
	v_fmamk_f32 v16, v22, 0x3f9837f0, v8
	v_fmamk_f32 v17, v18, 0x3f9837f0, v9
	v_fmamk_f32 v18, v23, 0x3f9837f0, v10
	v_cvt_pk_bf16_f32 v8, v12, v13
	v_cvt_pk_bf16_f32 v9, v14, v15
	v_cvt_pk_bf16_f32 v10, v16, v17
	v_cvt_pk_bf16_f32 v11, v18, v11
	v_lshl_add_u64 v[16:17], s[12:13], 0, v[32:33]
	global_store_dwordx4 v[16:17], v[8:11], off
	s_waitcnt vmcnt(6)
	s_nop 1
	v_mov_b32_e32 v12, v238
	v_mov_b32_e32 v13, v239
	v_mov_b32_e32 v14, v240
	v_mov_b32_e32 v15, v241
	s_nop 0
	v_lshlrev_b32_e32 v8, 16, v12
	v_and_b32_e32 v9, 0xffff0000, v12
	v_lshlrev_b32_e32 v10, 16, v13
	v_and_b32_e32 v11, 0xffff0000, v13
	v_lshlrev_b32_e32 v12, 16, v14
	v_and_b32_e32 v13, 0xffff0000, v14
	v_lshlrev_b32_e32 v14, 16, v15
	v_and_b32_e32 v15, 0xffff0000, v15
	v_fmac_f32_e32 v3, 0x3f9837f0, v15
	v_fmamk_f32 v4, v8, 0x3f9837f0, v4
	v_fmamk_f32 v5, v9, 0x3f9837f0, v5
	v_fmamk_f32 v6, v10, 0x3f9837f0, v6
	v_fmac_f32_e32 v7, 0x3f9837f0, v11
	v_fmamk_f32 v8, v12, 0x3f9837f0, v0
	v_fmamk_f32 v9, v13, 0x3f9837f0, v1
	v_fmamk_f32 v10, v14, 0x3f9837f0, v2
	v_cvt_pk_bf16_f32 v0, v4, v5
	v_cvt_pk_bf16_f32 v1, v6, v7
	v_cvt_pk_bf16_f32 v2, v8, v9
	v_cvt_pk_bf16_f32 v3, v10, v3
	global_store_dwordx4 v[16:17], v[0:3], off offset:256
	s_cbranch_vccnz .LBB0_1069
	s_andn2_b64 vcc, exec, s[10:11]
	s_cbranch_vccnz .LBB0_1068
	s_barrier
	s_branch .LBB0_1068

.LBB0_1166:
	ds_read_b128 v[0:3], v141
	ds_read_b128 v[4:7], v141 offset:1024
	ds_read_b128 v[8:11], v141 offset:2048
	ds_read_b128 v[12:15], v141 offset:3072
	ds_read_b128 v[16:19], v142
	ds_read_b128 v[20:23], v142 offset:1024
	ds_read_b128 v[24:27], v142 offset:2048
	ds_read_b128 v[28:31], v142 offset:3072
	s_add_u32 s46, s58, 0x40080
	s_addc_u32 s47, s59, 0
	s_add_i32 s71, s5, 0xc000
	v_lshl_add_u64 v[64:65], s[46:47], 0, v[134:135]
	s_mov_b32 m0, s71
	s_add_i32 s27, s5, 0xe000
	ds_read_b128 v[32:35], v143
	ds_read_b128 v[36:39], v143 offset:1024
	ds_read_b128 v[40:43], v143 offset:2048
	ds_read_b128 v[44:47], v143 offset:3072
	ds_read_b128 v[48:51], v143 offset:4096
	ds_read_b128 v[52:55], v143 offset:5120
	ds_read_b128 v[56:59], v143 offset:6144
	ds_read_b128 v[60:63], v143 offset:7168
	global_load_lds_dwordx4 v[64:65], off
	v_lshl_add_u64 v[64:65], s[46:47], 0, v[130:131]
	s_mov_b32 m0, s27
	s_nop 0
	global_load_lds_dwordx4 v[64:65], off
	s_nop 0
	s_waitcnt vmcnt(8)
	s_waitcnt lgkmcnt(0)
	s_barrier
	s_setprio 1
	s_waitcnt lgkmcnt(0)
	v_mfma_f32_16x16x32_bf16 v[64:67], v[0:3], v[32:35], 0
	v_mfma_f32_16x16x32_bf16 v[68:71], v[8:11], v[32:35], 0
	v_mfma_f32_16x16x32_bf16 v[72:75], v[0:3], v[40:43], 0
	v_mfma_f32_16x16x32_bf16 v[76:79], v[8:11], v[40:43], 0
	v_mfma_f32_16x16x32_bf16 v[80:83], v[0:3], v[48:51], 0
	v_mfma_f32_16x16x32_bf16 v[84:87], v[8:11], v[48:51], 0
	v_mfma_f32_16x16x32_bf16 v[88:91], v[0:3], v[56:59], 0
	v_mfma_f32_16x16x32_bf16 v[92:95], v[8:11], v[56:59], 0
	v_mfma_f32_16x16x32_bf16 v[64:67], v[4:7], v[36:39], v[64:67]
	v_mfma_f32_16x16x32_bf16 v[68:71], v[12:15], v[36:39], v[68:71]
	v_mfma_f32_16x16x32_bf16 v[72:75], v[4:7], v[44:47], v[72:75]
	v_mfma_f32_16x16x32_bf16 v[76:79], v[12:15], v[44:47], v[76:79]
	v_mfma_f32_16x16x32_bf16 v[80:83], v[4:7], v[52:55], v[80:83]
	v_mfma_f32_16x16x32_bf16 v[84:87], v[12:15], v[52:55], v[84:87]
	v_mfma_f32_16x16x32_bf16 v[88:91], v[4:7], v[60:63], v[88:91]
	v_mfma_f32_16x16x32_bf16 v[92:95], v[12:15], v[60:63], v[92:95]
	s_setprio 0
	s_setprio 1
	v_mfma_f32_16x16x32_bf16 v[96:99], v[16:19], v[32:35], 0
	v_mfma_f32_16x16x32_bf16 v[32:35], v[24:27], v[32:35], 0
	v_mfma_f32_16x16x32_bf16 v[96:99], v[20:23], v[36:39], v[96:99]
	v_mfma_f32_16x16x32_bf16 v[32:35], v[28:31], v[36:39], v[32:35]
	v_mfma_f32_16x16x32_bf16 v[36:39], v[16:19], v[40:43], 0
	v_mfma_f32_16x16x32_bf16 v[40:43], v[24:27], v[40:43], 0
	v_mfma_f32_16x16x32_bf16 v[36:39], v[20:23], v[44:47], v[36:39]
	v_mfma_f32_16x16x32_bf16 v[40:43], v[28:31], v[44:47], v[40:43]
	v_mfma_f32_16x16x32_bf16 v[44:47], v[16:19], v[48:51], 0
	v_mfma_f32_16x16x32_bf16 v[48:51], v[24:27], v[48:51], 0
	v_mfma_f32_16x16x32_bf16 v[44:47], v[20:23], v[52:55], v[44:47]
	v_mfma_f32_16x16x32_bf16 v[48:51], v[28:31], v[52:55], v[48:51]
	v_mfma_f32_16x16x32_bf16 v[52:55], v[16:19], v[56:59], 0
	v_mfma_f32_16x16x32_bf16 v[56:59], v[24:27], v[56:59], 0
	v_mfma_f32_16x16x32_bf16 v[52:55], v[20:23], v[60:63], v[52:55]
	v_mfma_f32_16x16x32_bf16 v[56:59], v[28:31], v[60:63], v[56:59]
	s_setprio 0
	s_barrier
	s_add_i32 s47, s64, s4
	v_lshl_add_u64 v[136:137], s[60:61], 0, v[132:133]
	s_add_i32 s29, s47, 0x2000
	v_lshl_add_u64 v[144:145], v[136:137], 0, s[16:17]
	s_mov_b32 m0, s47
	v_lshl_add_u64 v[196:197], s[60:61], 0, v[128:129]
	s_add_u32 s72, s60, 0x40100
	ds_read_b128 v[60:63], v143 offset:16384
	ds_read_b128 v[100:103], v143 offset:17408
	ds_read_b128 v[104:107], v143 offset:18432
	ds_read_b128 v[108:111], v143 offset:19456
	ds_read_b128 v[112:115], v143 offset:20480
	ds_read_b128 v[116:119], v143 offset:21504
	ds_read_b128 v[120:123], v143 offset:22528
	ds_read_b128 v[124:127], v143 offset:23552
	global_load_lds_dwordx4 v[144:145], off
	v_lshl_add_u64 v[144:145], v[196:197], 0, s[16:17]
	s_mov_b32 m0, s29
	s_addc_u32 s73, s61, 0
	s_add_i32 s31, s65, s4
	global_load_lds_dwordx4 v[144:145], off
	v_lshl_add_u64 v[144:145], s[72:73], 0, v[132:133]
	s_mov_b32 m0, s31
	s_add_i32 s46, s31, 0x2000
	global_load_lds_dwordx4 v[144:145], off
	v_lshl_add_u64 v[144:145], s[72:73], 0, v[128:129]
	s_mov_b32 m0, s46
	v_lshl_add_u64 v[210:211], s[58:59], 0, v[134:135]
	global_load_lds_dwordx4 v[144:145], off
	v_lshl_add_u64 v[144:145], v[210:211], 0, s[16:17]
	s_mov_b32 m0, s5
	v_lshl_add_u64 v[212:213], s[58:59], 0, v[130:131]
	global_load_lds_dwordx4 v[144:145], off
	v_lshl_add_u64 v[144:145], v[212:213], 0, s[16:17]
	s_mov_b32 m0, s35
	s_nop 0
	global_load_lds_dwordx4 v[144:145], off
	s_nop 0
	s_waitcnt vmcnt(8)
	s_waitcnt lgkmcnt(0)
	s_barrier
	s_setprio 1
	s_waitcnt lgkmcnt(0)
	v_mfma_f32_16x16x32_bf16 v[144:147], v[0:3], v[60:63], 0
	v_mfma_f32_16x16x32_bf16 v[152:155], v[0:3], v[104:107], 0
	v_mfma_f32_16x16x32_bf16 v[160:163], v[0:3], v[112:115], 0
	v_mfma_f32_16x16x32_bf16 v[0:3], v[0:3], v[120:123], 0
	v_mfma_f32_16x16x32_bf16 v[144:147], v[4:7], v[100:103], v[144:147]
	v_mfma_f32_16x16x32_bf16 v[152:155], v[4:7], v[108:111], v[152:155]
	v_mfma_f32_16x16x32_bf16 v[160:163], v[4:7], v[116:119], v[160:163]
	v_mfma_f32_16x16x32_bf16 v[0:3], v[4:7], v[124:127], v[0:3]
	v_mfma_f32_16x16x32_bf16 v[4:7], v[8:11], v[120:123], 0
	v_mfma_f32_16x16x32_bf16 v[148:151], v[8:11], v[60:63], 0
	v_mfma_f32_16x16x32_bf16 v[156:159], v[8:11], v[104:107], 0
	v_mfma_f32_16x16x32_bf16 v[164:167], v[8:11], v[112:115], 0
	v_mfma_f32_16x16x32_bf16 v[4:7], v[12:15], v[124:127], v[4:7]
	v_mfma_f32_16x16x32_bf16 v[148:151], v[12:15], v[100:103], v[148:151]
	v_mfma_f32_16x16x32_bf16 v[156:159], v[12:15], v[108:111], v[156:159]
	v_mfma_f32_16x16x32_bf16 v[164:167], v[12:15], v[116:119], v[164:167]
	s_setprio 0
	s_setprio 1
	v_mfma_f32_16x16x32_bf16 v[8:11], v[16:19], v[60:63], 0
	v_mfma_f32_16x16x32_bf16 v[12:15], v[24:27], v[60:63], 0
	v_mfma_f32_16x16x32_bf16 v[8:11], v[20:23], v[100:103], v[8:11]
	v_mfma_f32_16x16x32_bf16 v[12:15], v[28:31], v[100:103], v[12:15]
	v_mfma_f32_16x16x32_bf16 v[60:63], v[16:19], v[104:107], 0
	v_mfma_f32_16x16x32_bf16 v[100:103], v[24:27], v[104:107], 0
	v_mfma_f32_16x16x32_bf16 v[104:107], v[16:19], v[112:115], 0
	v_mfma_f32_16x16x32_bf16 v[16:19], v[16:19], v[120:123], 0
	v_mfma_f32_16x16x32_bf16 v[60:63], v[20:23], v[108:111], v[60:63]
	v_mfma_f32_16x16x32_bf16 v[100:103], v[28:31], v[108:111], v[100:103]
	v_mfma_f32_16x16x32_bf16 v[104:107], v[20:23], v[116:119], v[104:107]
	v_mfma_f32_16x16x32_bf16 v[108:111], v[24:27], v[112:115], 0
	v_mfma_f32_16x16x32_bf16 v[16:19], v[20:23], v[124:127], v[16:19]
	v_mfma_f32_16x16x32_bf16 v[20:23], v[24:27], v[120:123], 0
	v_mfma_f32_16x16x32_bf16 v[108:111], v[28:31], v[116:119], v[108:111]
	v_mfma_f32_16x16x32_bf16 v[20:23], v[28:31], v[124:127], v[20:23]
	s_setprio 0
	s_barrier
	s_add_i32 s70, 0, 0x18000
	s_add_i32 s76, 0, 0x1c000
	v_add_u32_e32 v222, s70, v138
	v_add_u32_e32 v230, s76, v138
	ds_read_b128 v[24:27], v222
	ds_read_b128 v[28:31], v222 offset:1024
	ds_read_b128 v[112:115], v222 offset:2048
	ds_read_b128 v[116:119], v222 offset:3072
	ds_read_b128 v[120:123], v230
	ds_read_b128 v[124:127], v230 offset:1024
	ds_read_b128 v[168:171], v230 offset:2048
	ds_read_b128 v[172:175], v230 offset:3072
	s_add_u32 s72, s58, 0x40100
	s_addc_u32 s73, s59, 0
	s_mov_b32 m0, s48
	v_lshl_add_u64 v[214:215], s[72:73], 0, v[134:135]
	ds_read_b128 v[176:179], v143 offset:32768
	ds_read_b128 v[180:183], v143 offset:33792
	ds_read_b128 v[184:187], v143 offset:34816
	ds_read_b128 v[188:191], v143 offset:35840
	ds_read_b128 v[192:195], v143 offset:36864
	ds_read_b128 v[198:201], v143 offset:37888
	ds_read_b128 v[202:205], v143 offset:38912
	ds_read_b128 v[206:209], v143 offset:39936
	global_load_lds_dwordx4 v[214:215], off
	v_lshl_add_u64 v[214:215], s[72:73], 0, v[130:131]
	s_mov_b32 m0, s49
	s_nop 0
	global_load_lds_dwordx4 v[214:215], off
	s_nop 0
	s_waitcnt vmcnt(8)
	s_waitcnt lgkmcnt(0)
	s_barrier
	s_setprio 1
	s_waitcnt lgkmcnt(0)
	v_mfma_f32_16x16x32_bf16 v[64:67], v[24:27], v[176:179], v[64:67]
	v_mfma_f32_16x16x32_bf16 v[68:71], v[112:115], v[176:179], v[68:71]
	v_mfma_f32_16x16x32_bf16 v[72:75], v[24:27], v[184:187], v[72:75]
	v_mfma_f32_16x16x32_bf16 v[76:79], v[112:115], v[184:187], v[76:79]
	v_mfma_f32_16x16x32_bf16 v[80:83], v[24:27], v[192:195], v[80:83]
	v_mfma_f32_16x16x32_bf16 v[84:87], v[112:115], v[192:195], v[84:87]
	v_mfma_f32_16x16x32_bf16 v[88:91], v[24:27], v[202:205], v[88:91]
	v_mfma_f32_16x16x32_bf16 v[92:95], v[112:115], v[202:205], v[92:95]
	v_mfma_f32_16x16x32_bf16 v[64:67], v[28:31], v[180:183], v[64:67]
	v_mfma_f32_16x16x32_bf16 v[68:71], v[116:119], v[180:183], v[68:71]
	v_mfma_f32_16x16x32_bf16 v[72:75], v[28:31], v[188:191], v[72:75]
	v_mfma_f32_16x16x32_bf16 v[76:79], v[116:119], v[188:191], v[76:79]
	v_mfma_f32_16x16x32_bf16 v[80:83], v[28:31], v[198:201], v[80:83]
	v_mfma_f32_16x16x32_bf16 v[84:87], v[116:119], v[198:201], v[84:87]
	v_mfma_f32_16x16x32_bf16 v[88:91], v[28:31], v[206:209], v[88:91]
	v_mfma_f32_16x16x32_bf16 v[92:95], v[116:119], v[206:209], v[92:95]
	s_setprio 0
	s_setprio 1
	v_mfma_f32_16x16x32_bf16 v[96:99], v[120:123], v[176:179], v[96:99]
	v_mfma_f32_16x16x32_bf16 v[32:35], v[168:171], v[176:179], v[32:35]
	v_mfma_f32_16x16x32_bf16 v[36:39], v[120:123], v[184:187], v[36:39]
	v_mfma_f32_16x16x32_bf16 v[40:43], v[168:171], v[184:187], v[40:43]
	v_mfma_f32_16x16x32_bf16 v[44:47], v[120:123], v[192:195], v[44:47]
	v_mfma_f32_16x16x32_bf16 v[48:51], v[168:171], v[192:195], v[48:51]
	v_mfma_f32_16x16x32_bf16 v[52:55], v[120:123], v[202:205], v[52:55]
	v_mfma_f32_16x16x32_bf16 v[56:59], v[168:171], v[202:205], v[56:59]
	v_mfma_f32_16x16x32_bf16 v[96:99], v[124:127], v[180:183], v[96:99]
	v_mfma_f32_16x16x32_bf16 v[32:35], v[172:175], v[180:183], v[32:35]
	v_mfma_f32_16x16x32_bf16 v[36:39], v[124:127], v[188:191], v[36:39]
	v_mfma_f32_16x16x32_bf16 v[40:43], v[172:175], v[188:191], v[40:43]
	v_mfma_f32_16x16x32_bf16 v[44:47], v[124:127], v[198:201], v[44:47]
	v_mfma_f32_16x16x32_bf16 v[48:51], v[172:175], v[198:201], v[48:51]
	v_mfma_f32_16x16x32_bf16 v[52:55], v[124:127], v[206:209], v[52:55]
	v_mfma_f32_16x16x32_bf16 v[56:59], v[172:175], v[206:209], v[56:59]
	s_setprio 0
	s_barrier
	s_add_i32 s72, s70, s4
	s_add_i32 s70, s72, 0x2000
	v_lshl_add_u64 v[136:137], v[136:137], 0, s[18:19]
	s_mov_b32 m0, s72
	s_add_u32 s74, s60, 0x40180
	ds_read_b128 v[176:179], v143 offset:49152
	ds_read_b128 v[180:183], v143 offset:50176
	ds_read_b128 v[184:187], v143 offset:51200
	ds_read_b128 v[188:191], v143 offset:52224
	ds_read_b128 v[192:195], v143 offset:53248
	ds_read_b128 v[198:201], v143 offset:54272
	ds_read_b128 v[202:205], v143 offset:55296
	ds_read_b128 v[206:209], v143 offset:56320
	global_load_lds_dwordx4 v[136:137], off
	v_lshl_add_u64 v[136:137], v[196:197], 0, s[18:19]
	s_mov_b32 m0, s70
	s_addc_u32 s75, s61, 0
	s_add_i32 s60, s76, s4
	global_load_lds_dwordx4 v[136:137], off
	v_lshl_add_u64 v[136:137], s[74:75], 0, v[132:133]
	s_mov_b32 m0, s60
	s_add_i32 s61, s60, 0x2000
	global_load_lds_dwordx4 v[136:137], off
	v_lshl_add_u64 v[136:137], s[74:75], 0, v[128:129]
	s_mov_b32 m0, s61
	s_nop 0
	global_load_lds_dwordx4 v[136:137], off
	v_lshl_add_u64 v[136:137], v[210:211], 0, s[18:19]
	s_mov_b32 m0, s53
	s_nop 0
	global_load_lds_dwordx4 v[136:137], off
	v_lshl_add_u64 v[136:137], v[212:213], 0, s[18:19]
	s_mov_b32 m0, s55
	s_nop 0
	global_load_lds_dwordx4 v[136:137], off
	s_nop 0
	s_waitcnt vmcnt(8)
	s_waitcnt lgkmcnt(0)
	s_barrier
	s_setprio 1
	s_waitcnt lgkmcnt(0)
	v_mfma_f32_16x16x32_bf16 v[0:3], v[24:27], v[202:205], v[0:3]
	v_mfma_f32_16x16x32_bf16 v[4:7], v[112:115], v[202:205], v[4:7]
	v_mfma_f32_16x16x32_bf16 v[144:147], v[24:27], v[176:179], v[144:147]
	v_mfma_f32_16x16x32_bf16 v[148:151], v[112:115], v[176:179], v[148:151]
	v_mfma_f32_16x16x32_bf16 v[152:155], v[24:27], v[184:187], v[152:155]
	v_mfma_f32_16x16x32_bf16 v[156:159], v[112:115], v[184:187], v[156:159]
	v_mfma_f32_16x16x32_bf16 v[160:163], v[24:27], v[192:195], v[160:163]
	v_mfma_f32_16x16x32_bf16 v[164:167], v[112:115], v[192:195], v[164:167]
	v_mfma_f32_16x16x32_bf16 v[0:3], v[28:31], v[206:209], v[0:3]
	v_mfma_f32_16x16x32_bf16 v[4:7], v[116:119], v[206:209], v[4:7]
	v_mfma_f32_16x16x32_bf16 v[144:147], v[28:31], v[180:183], v[144:147]
	v_mfma_f32_16x16x32_bf16 v[148:151], v[116:119], v[180:183], v[148:151]
	v_mfma_f32_16x16x32_bf16 v[152:155], v[28:31], v[188:191], v[152:155]
	v_mfma_f32_16x16x32_bf16 v[156:159], v[116:119], v[188:191], v[156:159]
	v_mfma_f32_16x16x32_bf16 v[160:163], v[28:31], v[198:201], v[160:163]
	v_mfma_f32_16x16x32_bf16 v[164:167], v[116:119], v[198:201], v[164:167]
	s_setprio 0
	s_setprio 1
	v_mfma_f32_16x16x32_bf16 v[8:11], v[120:123], v[176:179], v[8:11]
	v_mfma_f32_16x16x32_bf16 v[12:15], v[168:171], v[176:179], v[12:15]
	v_mfma_f32_16x16x32_bf16 v[24:27], v[120:123], v[184:187], v[60:63]
	v_mfma_f32_16x16x32_bf16 v[28:31], v[168:171], v[184:187], v[100:103]
	v_mfma_f32_16x16x32_bf16 v[60:63], v[120:123], v[192:195], v[104:107]
	v_mfma_f32_16x16x32_bf16 v[100:103], v[168:171], v[192:195], v[108:111]
	v_mfma_f32_16x16x32_bf16 v[16:19], v[120:123], v[202:205], v[16:19]
	v_mfma_f32_16x16x32_bf16 v[20:23], v[168:171], v[202:205], v[20:23]
	v_mfma_f32_16x16x32_bf16 v[8:11], v[124:127], v[180:183], v[8:11]
	v_mfma_f32_16x16x32_bf16 v[12:15], v[172:175], v[180:183], v[12:15]
	v_mfma_f32_16x16x32_bf16 v[24:27], v[124:127], v[188:191], v[24:27]
	v_mfma_f32_16x16x32_bf16 v[28:31], v[172:175], v[188:191], v[28:31]
	v_mfma_f32_16x16x32_bf16 v[60:63], v[124:127], v[198:201], v[60:63]
	v_mfma_f32_16x16x32_bf16 v[100:103], v[172:175], v[198:201], v[100:103]
	v_mfma_f32_16x16x32_bf16 v[16:19], v[124:127], v[206:209], v[16:19]
	v_mfma_f32_16x16x32_bf16 v[20:23], v[172:175], v[206:209], v[20:23]
	s_setprio 0
	s_barrier
	ds_read_b128 v[104:107], v141
	ds_read_b128 v[108:111], v141 offset:1024
	ds_read_b128 v[112:115], v141 offset:2048
	ds_read_b128 v[116:119], v141 offset:3072
	ds_read_b128 v[120:123], v142
	ds_read_b128 v[124:127], v142 offset:1024
	ds_read_b128 v[168:171], v142 offset:2048
	ds_read_b128 v[172:175], v142 offset:3072
	s_add_u32 s58, s58, 0x40180
	s_addc_u32 s59, s59, 0
	s_mov_b32 m0, s71
	v_lshl_add_u64 v[136:137], s[58:59], 0, v[134:135]
	ds_read_b128 v[176:179], v143
	ds_read_b128 v[180:183], v143 offset:1024
	ds_read_b128 v[184:187], v143 offset:2048
	ds_read_b128 v[188:191], v143 offset:3072
	ds_read_b128 v[192:195], v143 offset:4096
	ds_read_b128 v[198:201], v143 offset:5120
	ds_read_b128 v[202:205], v143 offset:6144
	ds_read_b128 v[206:209], v143 offset:7168
	global_load_lds_dwordx4 v[136:137], off
	v_lshl_add_u64 v[136:137], s[58:59], 0, v[130:131]
	s_mov_b32 m0, s27
	s_nop 0
	global_load_lds_dwordx4 v[136:137], off
	s_nop 0
	s_waitcnt vmcnt(8)
	s_waitcnt lgkmcnt(0)
	s_barrier
	s_setprio 1
	s_waitcnt lgkmcnt(0)
	v_mfma_f32_16x16x32_bf16 v[88:91], v[104:107], v[202:205], v[88:91]
	v_mfma_f32_16x16x32_bf16 v[64:67], v[104:107], v[176:179], v[64:67]
	v_mfma_f32_16x16x32_bf16 v[68:71], v[112:115], v[176:179], v[68:71]
	v_mfma_f32_16x16x32_bf16 v[72:75], v[104:107], v[184:187], v[72:75]
	v_mfma_f32_16x16x32_bf16 v[76:79], v[112:115], v[184:187], v[76:79]
	v_mfma_f32_16x16x32_bf16 v[80:83], v[104:107], v[192:195], v[80:83]
	v_mfma_f32_16x16x32_bf16 v[84:87], v[112:115], v[192:195], v[84:87]
	v_mfma_f32_16x16x32_bf16 v[210:213], v[108:111], v[206:209], v[88:91]
	v_mfma_f32_16x16x32_bf16 v[88:91], v[112:115], v[202:205], v[92:95]
	v_mfma_f32_16x16x32_bf16 v[64:67], v[108:111], v[180:183], v[64:67]
	v_mfma_f32_16x16x32_bf16 v[68:71], v[116:119], v[180:183], v[68:71]
	v_mfma_f32_16x16x32_bf16 v[72:75], v[108:111], v[188:191], v[72:75]
	v_mfma_f32_16x16x32_bf16 v[76:79], v[116:119], v[188:191], v[76:79]
	v_mfma_f32_16x16x32_bf16 v[80:83], v[108:111], v[198:201], v[80:83]
	v_mfma_f32_16x16x32_bf16 v[84:87], v[116:119], v[198:201], v[84:87]
	v_mfma_f32_16x16x32_bf16 v[92:95], v[116:119], v[206:209], v[88:91]
	s_setprio 0
	s_setprio 1
	v_mfma_f32_16x16x32_bf16 v[48:51], v[168:171], v[192:195], v[48:51]
	v_mfma_f32_16x16x32_bf16 v[88:91], v[120:123], v[176:179], v[96:99]
	v_mfma_f32_16x16x32_bf16 v[32:35], v[168:171], v[176:179], v[32:35]
	v_mfma_f32_16x16x32_bf16 v[36:39], v[120:123], v[184:187], v[36:39]
	v_mfma_f32_16x16x32_bf16 v[40:43], v[168:171], v[184:187], v[40:43]
	v_mfma_f32_16x16x32_bf16 v[44:47], v[120:123], v[192:195], v[44:47]
	v_mfma_f32_16x16x32_bf16 v[176:179], v[172:175], v[198:201], v[48:51]
	v_mfma_f32_16x16x32_bf16 v[48:51], v[120:123], v[202:205], v[52:55]
	v_mfma_f32_16x16x32_bf16 v[32:35], v[172:175], v[180:183], v[32:35]
	v_mfma_f32_16x16x32_bf16 v[36:39], v[124:127], v[188:191], v[36:39]
	v_mfma_f32_16x16x32_bf16 v[40:43], v[172:175], v[188:191], v[40:43]
	v_mfma_f32_16x16x32_bf16 v[44:47], v[124:127], v[198:201], v[44:47]
	v_mfma_f32_16x16x32_bf16 v[52:55], v[124:127], v[206:209], v[48:51]
	v_mfma_f32_16x16x32_bf16 v[48:51], v[168:171], v[202:205], v[56:59]
	v_mfma_f32_16x16x32_bf16 v[214:217], v[124:127], v[180:183], v[88:91]
	v_mfma_f32_16x16x32_bf16 v[180:183], v[172:175], v[206:209], v[48:51]
	s_setprio 0
	s_barrier
	s_mov_b32 m0, s47
	v_lshl_add_u64 v[136:137], s[42:43], 0, v[132:133]
	s_add_u32 s58, s42, 0x40000
	s_nop 0
	ds_read_b128 v[48:51], v143 offset:16384
	ds_read_b128 v[56:59], v143 offset:17408
	ds_read_b128 v[88:91], v143 offset:18432
	ds_read_b128 v[96:99], v143 offset:19456
	ds_read_b128 v[184:187], v143 offset:20480
	ds_read_b128 v[188:191], v143 offset:21504
	ds_read_b128 v[192:195], v143 offset:22528
	ds_read_b128 v[198:201], v143 offset:23552
	global_load_lds_dwordx4 v[136:137], off
	v_lshl_add_u64 v[196:197], s[42:43], 0, v[128:129]
	s_mov_b32 m0, s29
	s_addc_u32 s59, s43, 0
	global_load_lds_dwordx4 v[196:197], off
	v_lshl_add_u64 v[202:203], s[58:59], 0, v[132:133]
	s_mov_b32 m0, s31
	v_lshl_add_u64 v[250:251], s[40:41], 0, v[134:135]
	global_load_lds_dwordx4 v[202:203], off
	v_lshl_add_u64 v[202:203], s[58:59], 0, v[128:129]
	s_mov_b32 m0, s46
	v_lshl_add_u64 v[252:253], s[40:41], 0, v[130:131]
	global_load_lds_dwordx4 v[202:203], off
	s_mov_b32 m0, s5
	s_nop 0
	global_load_lds_dwordx4 v[250:251], off
	s_mov_b32 m0, s35
	s_nop 0
	global_load_lds_dwordx4 v[252:253], off
	s_nop 0
	s_waitcnt vmcnt(8)
	s_waitcnt lgkmcnt(0)
	s_barrier
	s_setprio 1
	s_waitcnt lgkmcnt(0)
	v_mfma_f32_16x16x32_bf16 v[0:3], v[104:107], v[192:195], v[0:3]
	v_mfma_f32_16x16x32_bf16 v[4:7], v[112:115], v[192:195], v[4:7]
	v_mfma_f32_16x16x32_bf16 v[144:147], v[104:107], v[48:51], v[144:147]
	v_mfma_f32_16x16x32_bf16 v[148:151], v[112:115], v[48:51], v[148:151]
	v_mfma_f32_16x16x32_bf16 v[152:155], v[104:107], v[88:91], v[152:155]
	v_mfma_f32_16x16x32_bf16 v[156:159], v[112:115], v[88:91], v[156:159]
	v_mfma_f32_16x16x32_bf16 v[160:163], v[104:107], v[184:187], v[160:163]
	v_mfma_f32_16x16x32_bf16 v[164:167], v[112:115], v[184:187], v[164:167]
	v_mfma_f32_16x16x32_bf16 v[0:3], v[108:111], v[198:201], v[0:3]
	v_mfma_f32_16x16x32_bf16 v[4:7], v[116:119], v[198:201], v[4:7]
	v_mfma_f32_16x16x32_bf16 v[144:147], v[108:111], v[56:59], v[144:147]
	v_mfma_f32_16x16x32_bf16 v[148:151], v[116:119], v[56:59], v[148:151]
	v_mfma_f32_16x16x32_bf16 v[152:155], v[108:111], v[96:99], v[152:155]
	v_mfma_f32_16x16x32_bf16 v[156:159], v[116:119], v[96:99], v[156:159]
	v_mfma_f32_16x16x32_bf16 v[160:163], v[108:111], v[188:191], v[160:163]
	v_mfma_f32_16x16x32_bf16 v[164:167], v[116:119], v[188:191], v[164:167]
	s_setprio 0
	s_setprio 1
	v_mfma_f32_16x16x32_bf16 v[12:15], v[168:171], v[48:51], v[12:15]
	v_mfma_f32_16x16x32_bf16 v[202:205], v[172:175], v[56:59], v[12:15]
	v_mfma_f32_16x16x32_bf16 v[12:15], v[120:123], v[88:91], v[24:27]
	v_mfma_f32_16x16x32_bf16 v[24:27], v[124:127], v[96:99], v[12:15]
	v_mfma_f32_16x16x32_bf16 v[12:15], v[168:171], v[88:91], v[28:31]
	v_mfma_f32_16x16x32_bf16 v[206:209], v[172:175], v[96:99], v[12:15]
	v_mfma_f32_16x16x32_bf16 v[12:15], v[120:123], v[184:187], v[60:63]
	v_mfma_f32_16x16x32_bf16 v[218:221], v[124:127], v[188:191], v[12:15]
	v_mfma_f32_16x16x32_bf16 v[12:15], v[168:171], v[184:187], v[100:103]
	v_mfma_f32_16x16x32_bf16 v[8:11], v[120:123], v[48:51], v[8:11]
	v_mfma_f32_16x16x32_bf16 v[184:187], v[172:175], v[188:191], v[12:15]
	v_mfma_f32_16x16x32_bf16 v[12:15], v[120:123], v[192:195], v[16:19]
	v_mfma_f32_16x16x32_bf16 v[8:11], v[124:127], v[56:59], v[8:11]
	v_mfma_f32_16x16x32_bf16 v[188:191], v[124:127], v[198:201], v[12:15]
	v_mfma_f32_16x16x32_bf16 v[12:15], v[168:171], v[192:195], v[20:23]
	v_mfma_f32_16x16x32_bf16 v[168:171], v[172:175], v[198:201], v[12:15]
	s_setprio 0
	s_barrier
	s_nop 4
	ds_read_b128 v[12:15], v222
	ds_read_b128 v[16:19], v222 offset:1024
	ds_read_b128 v[172:175], v222 offset:2048
	ds_read_b128 v[192:195], v222 offset:3072
	ds_read_b128 v[198:201], v230
	ds_read_b128 v[222:225], v230 offset:1024
	ds_read_b128 v[226:229], v230 offset:2048
	ds_read_b128 v[230:233], v230 offset:3072
	s_add_u32 s46, s40, 0x40000
	s_addc_u32 s47, s41, 0
	s_mov_b32 m0, s48
	v_lshl_add_u64 v[48:49], s[46:47], 0, v[134:135]
	ds_read_b128 v[20:23], v143 offset:32768
	ds_read_b128 v[28:31], v143 offset:33792
	ds_read_b128 v[60:63], v143 offset:34816
	ds_read_b128 v[100:103], v143 offset:35840
	ds_read_b128 v[234:237], v143 offset:36864
	ds_read_b128 v[238:241], v143 offset:37888
	ds_read_b128 v[242:245], v143 offset:38912
	ds_read_b128 v[246:249], v143 offset:39936
	global_load_lds_dwordx4 v[48:49], off
	v_lshl_add_u64 v[48:49], s[46:47], 0, v[130:131]
	s_mov_b32 m0, s49
	s_nop 0
	global_load_lds_dwordx4 v[48:49], off
	s_waitcnt vmcnt(8)
	s_waitcnt lgkmcnt(0)
	s_barrier
	s_setprio 1
	s_waitcnt lgkmcnt(0)
	v_mfma_f32_16x16x32_bf16 v[48:51], v[12:15], v[20:23], v[64:67]
	v_mfma_f32_16x16x32_bf16 v[120:123], v[16:19], v[28:31], v[48:51]
	v_mfma_f32_16x16x32_bf16 v[48:51], v[172:175], v[20:23], v[68:71]
	v_mfma_f32_16x16x32_bf16 v[112:115], v[192:195], v[28:31], v[48:51]
	v_mfma_f32_16x16x32_bf16 v[48:51], v[12:15], v[60:63], v[72:75]
	v_mfma_f32_16x16x32_bf16 v[104:107], v[16:19], v[100:103], v[48:51]
	v_mfma_f32_16x16x32_bf16 v[48:51], v[172:175], v[60:63], v[76:79]
	v_mfma_f32_16x16x32_bf16 v[96:99], v[192:195], v[100:103], v[48:51]
	v_mfma_f32_16x16x32_bf16 v[48:51], v[12:15], v[234:237], v[80:83]
	v_mfma_f32_16x16x32_bf16 v[88:91], v[16:19], v[238:241], v[48:51]
	v_mfma_f32_16x16x32_bf16 v[48:51], v[172:175], v[234:237], v[84:87]
	v_mfma_f32_16x16x32_bf16 v[80:83], v[192:195], v[238:241], v[48:51]
	v_mfma_f32_16x16x32_bf16 v[48:51], v[12:15], v[242:245], v[210:213]
	v_mfma_f32_16x16x32_bf16 v[56:59], v[16:19], v[246:249], v[48:51]
	v_mfma_f32_16x16x32_bf16 v[48:51], v[172:175], v[242:245], v[92:95]
	v_mfma_f32_16x16x32_bf16 v[48:51], v[192:195], v[246:249], v[48:51]
	s_setprio 0
	s_setprio 1
	v_mfma_f32_16x16x32_bf16 v[64:67], v[198:201], v[20:23], v[214:217]
	v_mfma_f32_16x16x32_bf16 v[20:23], v[226:229], v[20:23], v[32:35]
	v_mfma_f32_16x16x32_bf16 v[116:119], v[230:233], v[28:31], v[20:23]
	v_mfma_f32_16x16x32_bf16 v[20:23], v[198:201], v[60:63], v[36:39]
	v_mfma_f32_16x16x32_bf16 v[108:111], v[222:225], v[100:103], v[20:23]
	v_mfma_f32_16x16x32_bf16 v[20:23], v[226:229], v[60:63], v[40:43]
	v_mfma_f32_16x16x32_bf16 v[100:103], v[230:233], v[100:103], v[20:23]
	v_mfma_f32_16x16x32_bf16 v[20:23], v[198:201], v[234:237], v[44:47]
	v_mfma_f32_16x16x32_bf16 v[92:95], v[222:225], v[238:241], v[20:23]
	v_mfma_f32_16x16x32_bf16 v[20:23], v[226:229], v[234:237], v[176:179]
	v_mfma_f32_16x16x32_bf16 v[84:87], v[230:233], v[238:241], v[20:23]
	v_mfma_f32_16x16x32_bf16 v[20:23], v[198:201], v[242:245], v[52:55]
	v_mfma_f32_16x16x32_bf16 v[60:63], v[222:225], v[246:249], v[20:23]
	v_mfma_f32_16x16x32_bf16 v[20:23], v[226:229], v[242:245], v[180:183]
	v_mfma_f32_16x16x32_bf16 v[124:127], v[222:225], v[28:31], v[64:67]
	v_mfma_f32_16x16x32_bf16 v[52:55], v[230:233], v[246:249], v[20:23]
	s_setprio 0
	s_barrier
	s_mov_b32 m0, s72
	s_nop 2
	v_lshl_add_u64 v[20:21], v[136:137], 0, s[12:13]
	s_add_u32 s46, s42, 0x40080
	ds_read_b128 v[32:35], v143 offset:49152
	ds_read_b128 v[40:43], v143 offset:50176
	ds_read_b128 v[176:179], v143 offset:51200
	ds_read_b128 v[180:183], v143 offset:52224
	ds_read_b128 v[210:213], v143 offset:53248
	ds_read_b128 v[214:217], v143 offset:54272
	ds_read_b128 v[234:237], v143 offset:55296
	ds_read_b128 v[238:241], v143 offset:56320
	global_load_lds_dwordx4 v[20:21], off
	v_lshl_add_u64 v[20:21], v[196:197], 0, s[12:13]
	s_mov_b32 m0, s70
	s_addc_u32 s47, s43, 0
	global_load_lds_dwordx4 v[20:21], off
	v_lshl_add_u64 v[20:21], s[46:47], 0, v[132:133]
	s_mov_b32 m0, s60
	s_nop 0
	global_load_lds_dwordx4 v[20:21], off
	v_lshl_add_u64 v[20:21], s[46:47], 0, v[128:129]
	s_mov_b32 m0, s61
	s_nop 0
	global_load_lds_dwordx4 v[20:21], off
	v_lshl_add_u64 v[20:21], v[250:251], 0, s[12:13]
	s_mov_b32 m0, s53
	s_nop 0
	global_load_lds_dwordx4 v[20:21], off
	v_lshl_add_u64 v[20:21], v[252:253], 0, s[12:13]
	s_mov_b32 m0, s55
	s_nop 0
	global_load_lds_dwordx4 v[20:21], off
	s_nop 0
	s_waitcnt vmcnt(8)
	s_waitcnt lgkmcnt(0)
	s_barrier
	s_setprio 1
	s_waitcnt lgkmcnt(0)
	v_mfma_f32_16x16x32_bf16 v[20:23], v[12:15], v[32:35], v[144:147]
	v_mfma_f32_16x16x32_bf16 v[76:79], v[16:19], v[40:43], v[20:23]
	v_mfma_f32_16x16x32_bf16 v[20:23], v[172:175], v[32:35], v[148:151]
	v_mfma_f32_16x16x32_bf16 v[68:71], v[192:195], v[40:43], v[20:23]
	v_mfma_f32_16x16x32_bf16 v[20:23], v[12:15], v[176:179], v[152:155]
	v_mfma_f32_16x16x32_bf16 v[44:47], v[16:19], v[180:183], v[20:23]
	v_mfma_f32_16x16x32_bf16 v[20:23], v[172:175], v[176:179], v[156:159]
	v_mfma_f32_16x16x32_bf16 v[36:39], v[192:195], v[180:183], v[20:23]
	v_mfma_f32_16x16x32_bf16 v[20:23], v[12:15], v[210:213], v[160:163]
	v_mfma_f32_16x16x32_bf16 v[0:3], v[12:15], v[234:237], v[0:3]
	v_mfma_f32_16x16x32_bf16 v[28:31], v[16:19], v[214:217], v[20:23]
	v_mfma_f32_16x16x32_bf16 v[20:23], v[172:175], v[210:213], v[164:167]
	v_mfma_f32_16x16x32_bf16 v[12:15], v[16:19], v[238:241], v[0:3]
	v_mfma_f32_16x16x32_bf16 v[0:3], v[172:175], v[234:237], v[4:7]
	v_mfma_f32_16x16x32_bf16 v[20:23], v[192:195], v[214:217], v[20:23]
	v_mfma_f32_16x16x32_bf16 v[4:7], v[192:195], v[238:241], v[0:3]
	s_setprio 0
	s_setprio 1
	v_mfma_f32_16x16x32_bf16 v[0:3], v[198:201], v[32:35], v[8:11]
	v_mfma_f32_16x16x32_bf16 v[72:75], v[222:225], v[40:43], v[0:3]
	v_mfma_f32_16x16x32_bf16 v[0:3], v[226:229], v[32:35], v[202:205]
	v_mfma_f32_16x16x32_bf16 v[64:67], v[230:233], v[40:43], v[0:3]
	v_mfma_f32_16x16x32_bf16 v[0:3], v[198:201], v[176:179], v[24:27]
	v_mfma_f32_16x16x32_bf16 v[40:43], v[222:225], v[180:183], v[0:3]
	v_mfma_f32_16x16x32_bf16 v[0:3], v[226:229], v[176:179], v[206:209]
	v_mfma_f32_16x16x32_bf16 v[32:35], v[230:233], v[180:183], v[0:3]
	v_mfma_f32_16x16x32_bf16 v[0:3], v[198:201], v[210:213], v[218:221]
	v_mfma_f32_16x16x32_bf16 v[24:27], v[222:225], v[214:217], v[0:3]
	v_mfma_f32_16x16x32_bf16 v[0:3], v[226:229], v[210:213], v[184:187]
	v_mfma_f32_16x16x32_bf16 v[16:19], v[230:233], v[214:217], v[0:3]
	v_mfma_f32_16x16x32_bf16 v[0:3], v[198:201], v[234:237], v[188:191]
	v_mfma_f32_16x16x32_bf16 v[8:11], v[222:225], v[238:241], v[0:3]
	v_mfma_f32_16x16x32_bf16 v[0:3], v[226:229], v[234:237], v[168:171]
	v_mfma_f32_16x16x32_bf16 v[0:3], v[230:233], v[238:241], v[0:3]
	s_setprio 0
	s_barrier
	s_andn2_b64 vcc, exec, s[14:15]
	s_cbranch_vccnz .LBB0_1168
	s_barrier

.LBB0_1587:
	v_lshl_add_u32 v148, s35, 8, v151
	v_lshl_or_b32 v146, s64, 8, v153
	v_ashrrev_i32_e32 v149, 31, v148
	v_ashrrev_i32_e32 v147, 31, v146
	v_lshlrev_b64 v[144:145], 10, v[148:149]
	v_lshl_add_u64 v[144:145], v[144:145], 0, v[146:147]
	v_lshlrev_b64 v[144:145], 1, v[144:145]
	v_lshl_add_u64 v[162:163], s[14:15], 0, v[144:145]
	v_mov_b64_e32 v[252:253], v[162:163]
	global_load_dwordx4 v[226:229], v[252:253], off
	global_load_dwordx4 v[230:233], v[252:253], off offset:256
	s_mov_b64 s[98:99], 0x8000
	v_lshl_add_u64 v[250:251], v[252:253], 0, s[98:99]
	global_load_dwordx4 v[234:237], v[250:251], off
	global_load_dwordx4 v[238:241], v[250:251], off offset:256
	s_mov_b64 s[98:99], 0x10000
	v_lshl_add_u64 v[250:251], v[252:253], 0, s[98:99]
	global_load_dwordx4 v[242:245], v[250:251], off
	global_load_dwordx4 v[246:249], v[250:251], off offset:256
	s_and_b64 vcc, exec, s[6:7]
	s_mov_b64 s[6:7], -1
	s_waitcnt vmcnt(5)
	s_nop 1
	v_mov_b32_e32 v158, v226
	v_mov_b32_e32 v159, v227
	v_mov_b32_e32 v160, v228
	v_mov_b32_e32 v161, v229
	s_mov_b64 s[98:99], 0x18000
	v_lshl_add_u64 v[250:251], v[252:253], 0, s[98:99]
	global_load_dwordx4 v[226:229], v[250:251], off
	v_lshlrev_b32_e32 v149, 16, v158
	v_and_b32_e32 v157, 0xffff0000, v158
	v_lshlrev_b32_e32 v158, 16, v159
	v_and_b32_e32 v159, 0xffff0000, v159
	v_lshlrev_b32_e32 v165, 16, v161
	v_and_b32_e32 v161, 0xffff0000, v161
	v_lshlrev_b32_e32 v164, 16, v160
	v_and_b32_e32 v160, 0xffff0000, v160
	v_fmamk_f32 v124, v149, 0x3f9837f0, v124
	v_fmamk_f32 v125, v157, 0x3f9837f0, v125
	v_fmamk_f32 v126, v158, 0x3f9837f0, v126
	v_fmac_f32_e32 v127, 0x3f9837f0, v159
	v_fmac_f32_e32 v123, 0x3f9837f0, v161
	v_fmamk_f32 v149, v164, 0x3f9837f0, v120
	v_fmamk_f32 v157, v160, 0x3f9837f0, v121
	v_fmamk_f32 v158, v165, 0x3f9837f0, v122
	v_cvt_pk_bf16_f32 v120, v124, v125
	v_cvt_pk_bf16_f32 v121, v126, v127
	v_cvt_pk_bf16_f32 v122, v149, v157
	v_cvt_pk_bf16_f32 v123, v158, v123
	v_or_b32_e32 v158, 16, v148
	v_ashrrev_i32_e32 v159, 31, v158
	v_lshlrev_b64 v[158:159], 10, v[158:159]
	v_lshl_add_u64 v[160:161], s[12:13], 0, v[144:145]
	v_lshl_add_u64 v[158:159], v[158:159], 0, v[146:147]
	global_store_dwordx4 v[160:161], v[120:123], off
	v_lshlrev_b64 v[158:159], 1, v[158:159]
	v_lshl_add_u64 v[162:163], s[14:15], 0, v[158:159]
	s_waitcnt vmcnt(6)
	s_nop 1
	v_mov_b32_e32 v124, v230
	v_mov_b32_e32 v125, v231
	v_mov_b32_e32 v126, v232
	v_mov_b32_e32 v127, v233
	global_load_dwordx4 v[230:233], v[250:251], off offset:256
	v_lshlrev_b32_e32 v120, 16, v124
	v_and_b32_e32 v121, 0xffff0000, v124
	v_lshlrev_b32_e32 v122, 16, v125
	v_and_b32_e32 v123, 0xffff0000, v125
	v_lshlrev_b32_e32 v124, 16, v126
	v_and_b32_e32 v125, 0xffff0000, v126
	v_lshlrev_b32_e32 v126, 16, v127
	v_and_b32_e32 v127, 0xffff0000, v127
	v_fmac_f32_e32 v115, 0x3f9837f0, v127
	v_fmamk_f32 v116, v120, 0x3f9837f0, v116
	v_fmamk_f32 v117, v121, 0x3f9837f0, v117
	v_fmamk_f32 v118, v122, 0x3f9837f0, v118
	v_fmac_f32_e32 v119, 0x3f9837f0, v123
	v_fmamk_f32 v120, v124, 0x3f9837f0, v112
	v_fmamk_f32 v121, v125, 0x3f9837f0, v113
	v_fmamk_f32 v122, v126, 0x3f9837f0, v114
	v_cvt_pk_bf16_f32 v112, v116, v117
	v_cvt_pk_bf16_f32 v113, v118, v119
	v_cvt_pk_bf16_f32 v114, v120, v121
	v_cvt_pk_bf16_f32 v115, v122, v115
	global_store_dwordx4 v[160:161], v[112:115], off offset:256
	s_waitcnt vmcnt(7)
	s_nop 1
	v_mov_b32_e32 v112, v234
	v_mov_b32_e32 v113, v235
	v_mov_b32_e32 v114, v236
	v_mov_b32_e32 v115, v237
	s_mov_b64 s[98:99], 0x40000
	v_lshl_add_u64 v[250:251], v[252:253], 0, s[98:99]
	global_load_dwordx4 v[234:237], v[250:251], off
	v_lshlrev_b32_e32 v116, 16, v112
	v_and_b32_e32 v112, 0xffff0000, v112
	v_lshlrev_b32_e32 v117, 16, v113
	v_and_b32_e32 v113, 0xffff0000, v113
	v_lshlrev_b32_e32 v119, 16, v115
	v_and_b32_e32 v115, 0xffff0000, v115
	v_lshlrev_b32_e32 v118, 16, v114
	v_and_b32_e32 v114, 0xffff0000, v114
	v_fmamk_f32 v108, v116, 0x3f9837f0, v108
	v_fmamk_f32 v109, v112, 0x3f9837f0, v109
	v_fmamk_f32 v110, v117, 0x3f9837f0, v110
	v_fmac_f32_e32 v111, 0x3f9837f0, v113
	v_fmac_f32_e32 v107, 0x3f9837f0, v115
	v_fmamk_f32 v112, v118, 0x3f9837f0, v104
	v_fmamk_f32 v113, v114, 0x3f9837f0, v105
	v_fmamk_f32 v114, v119, 0x3f9837f0, v106
	v_cvt_pk_bf16_f32 v104, v108, v109
	v_cvt_pk_bf16_f32 v105, v110, v111
	v_cvt_pk_bf16_f32 v106, v112, v113
	v_cvt_pk_bf16_f32 v107, v114, v107
	v_or_b32_e32 v112, 32, v148
	v_ashrrev_i32_e32 v113, 31, v112
	v_lshlrev_b64 v[112:113], 10, v[112:113]
	v_lshl_add_u64 v[114:115], s[12:13], 0, v[158:159]
	v_lshl_add_u64 v[112:113], v[112:113], 0, v[146:147]
	global_store_dwordx4 v[114:115], v[104:107], off
	v_lshlrev_b64 v[112:113], 1, v[112:113]
	v_lshl_add_u64 v[116:117], s[14:15], 0, v[112:113]
	s_waitcnt vmcnt(8)
	s_nop 1
	v_mov_b32_e32 v108, v238
	v_mov_b32_e32 v109, v239
	v_mov_b32_e32 v110, v240
	v_mov_b32_e32 v111, v241
	global_load_dwordx4 v[238:241], v[250:251], off offset:256
	v_lshlrev_b32_e32 v104, 16, v108
	v_and_b32_e32 v105, 0xffff0000, v108
	v_lshlrev_b32_e32 v106, 16, v109
	v_and_b32_e32 v107, 0xffff0000, v109
	v_lshlrev_b32_e32 v108, 16, v110
	v_and_b32_e32 v109, 0xffff0000, v110
	v_lshlrev_b32_e32 v110, 16, v111
	v_and_b32_e32 v111, 0xffff0000, v111
	v_fmac_f32_e32 v99, 0x3f9837f0, v111
	v_fmamk_f32 v100, v104, 0x3f9837f0, v100
	v_fmamk_f32 v101, v105, 0x3f9837f0, v101
	v_fmamk_f32 v102, v106, 0x3f9837f0, v102
	v_fmac_f32_e32 v103, 0x3f9837f0, v107
	v_fmamk_f32 v104, v108, 0x3f9837f0, v96
	v_fmamk_f32 v105, v109, 0x3f9837f0, v97
	v_fmamk_f32 v106, v110, 0x3f9837f0, v98
	v_cvt_pk_bf16_f32 v96, v100, v101
	v_cvt_pk_bf16_f32 v97, v102, v103
	v_cvt_pk_bf16_f32 v98, v104, v105
	v_cvt_pk_bf16_f32 v99, v106, v99
	global_store_dwordx4 v[114:115], v[96:99], off offset:256
	s_waitcnt vmcnt(9)
	s_nop 1
	v_mov_b32_e32 v96, v242
	v_mov_b32_e32 v97, v243
	v_mov_b32_e32 v98, v244
	v_mov_b32_e32 v99, v245
	s_mov_b64 s[98:99], 0x48000
	v_lshl_add_u64 v[250:251], v[252:253], 0, s[98:99]
	global_load_dwordx4 v[242:245], v[250:251], off
	v_lshlrev_b32_e32 v100, 16, v96
	v_and_b32_e32 v96, 0xffff0000, v96
	v_lshlrev_b32_e32 v101, 16, v97
	v_and_b32_e32 v97, 0xffff0000, v97
	v_lshlrev_b32_e32 v103, 16, v99
	v_and_b32_e32 v99, 0xffff0000, v99
	v_lshlrev_b32_e32 v102, 16, v98
	v_and_b32_e32 v98, 0xffff0000, v98
	v_fmamk_f32 v92, v100, 0x3f9837f0, v92
	v_fmamk_f32 v93, v96, 0x3f9837f0, v93
	v_fmamk_f32 v94, v101, 0x3f9837f0, v94
	v_fmac_f32_e32 v95, 0x3f9837f0, v97
	v_fmac_f32_e32 v91, 0x3f9837f0, v99
	v_fmamk_f32 v96, v102, 0x3f9837f0, v88
	v_fmamk_f32 v97, v98, 0x3f9837f0, v89
	v_fmamk_f32 v98, v103, 0x3f9837f0, v90
	v_cvt_pk_bf16_f32 v88, v92, v93
	v_cvt_pk_bf16_f32 v89, v94, v95
	v_cvt_pk_bf16_f32 v90, v96, v97
	v_cvt_pk_bf16_f32 v91, v98, v91
	v_or_b32_e32 v96, 48, v148
	v_ashrrev_i32_e32 v97, 31, v96
	v_lshlrev_b64 v[96:97], 10, v[96:97]
	v_lshl_add_u64 v[98:99], s[12:13], 0, v[112:113]
	v_lshl_add_u64 v[96:97], v[96:97], 0, v[146:147]
	global_store_dwordx4 v[98:99], v[88:91], off
	v_lshlrev_b64 v[96:97], 1, v[96:97]
	v_lshl_add_u64 v[100:101], s[14:15], 0, v[96:97]
	s_waitcnt vmcnt(10)
	s_nop 1
	v_mov_b32_e32 v92, v246
	v_mov_b32_e32 v93, v247
	v_mov_b32_e32 v94, v248
	v_mov_b32_e32 v95, v249
	global_load_dwordx4 v[246:249], v[250:251], off offset:256
	v_lshlrev_b32_e32 v88, 16, v92
	v_and_b32_e32 v89, 0xffff0000, v92
	v_lshlrev_b32_e32 v90, 16, v93
	v_and_b32_e32 v91, 0xffff0000, v93
	v_lshlrev_b32_e32 v92, 16, v94
	v_and_b32_e32 v93, 0xffff0000, v94
	v_lshlrev_b32_e32 v94, 16, v95
	v_and_b32_e32 v95, 0xffff0000, v95
	v_fmac_f32_e32 v83, 0x3f9837f0, v95
	v_fmamk_f32 v84, v88, 0x3f9837f0, v84
	v_fmamk_f32 v85, v89, 0x3f9837f0, v85
	v_fmamk_f32 v86, v90, 0x3f9837f0, v86
	v_fmac_f32_e32 v87, 0x3f9837f0, v91
	v_fmamk_f32 v88, v92, 0x3f9837f0, v80
	v_fmamk_f32 v89, v93, 0x3f9837f0, v81
	v_fmamk_f32 v90, v94, 0x3f9837f0, v82
	v_cvt_pk_bf16_f32 v80, v84, v85
	v_cvt_pk_bf16_f32 v81, v86, v87
	v_cvt_pk_bf16_f32 v82, v88, v89
	v_cvt_pk_bf16_f32 v83, v90, v83
	global_store_dwordx4 v[98:99], v[80:83], off offset:256
	s_waitcnt vmcnt(11)
	s_nop 1
	v_mov_b32_e32 v80, v226
	v_mov_b32_e32 v81, v227
	v_mov_b32_e32 v82, v228
	v_mov_b32_e32 v83, v229
	s_mov_b64 s[98:99], 0x50000
	v_lshl_add_u64 v[250:251], v[252:253], 0, s[98:99]
	global_load_dwordx4 v[226:229], v[250:251], off
	v_lshlrev_b32_e32 v84, 16, v80
	v_and_b32_e32 v80, 0xffff0000, v80
	v_lshlrev_b32_e32 v85, 16, v81
	v_and_b32_e32 v81, 0xffff0000, v81
	v_lshlrev_b32_e32 v87, 16, v83
	v_and_b32_e32 v83, 0xffff0000, v83
	v_lshlrev_b32_e32 v86, 16, v82
	v_and_b32_e32 v82, 0xffff0000, v82
	v_fmamk_f32 v76, v84, 0x3f9837f0, v76
	v_fmamk_f32 v77, v80, 0x3f9837f0, v77
	v_fmamk_f32 v78, v85, 0x3f9837f0, v78
	v_fmac_f32_e32 v79, 0x3f9837f0, v81
	v_fmac_f32_e32 v75, 0x3f9837f0, v83
	v_fmamk_f32 v80, v86, 0x3f9837f0, v72
	v_fmamk_f32 v81, v82, 0x3f9837f0, v73
	v_fmamk_f32 v82, v87, 0x3f9837f0, v74
	v_cvt_pk_bf16_f32 v72, v76, v77
	v_cvt_pk_bf16_f32 v73, v78, v79
	v_cvt_pk_bf16_f32 v74, v80, v81
	v_cvt_pk_bf16_f32 v75, v82, v75
	v_lshl_add_u64 v[82:83], s[12:13], 0, v[96:97]
	global_store_dwordx4 v[82:83], v[72:75], off
	v_lshl_add_u64 v[80:81], v[144:145], 0, s[20:21]
	v_lshl_add_u64 v[84:85], s[14:15], 0, v[80:81]
	s_waitcnt vmcnt(11)
	s_nop 1
	v_mov_b32_e32 v76, v230
	v_mov_b32_e32 v77, v231
	v_mov_b32_e32 v78, v232
	v_mov_b32_e32 v79, v233
	global_load_dwordx4 v[230:233], v[250:251], off offset:256
	v_lshlrev_b32_e32 v72, 16, v76
	v_and_b32_e32 v73, 0xffff0000, v76
	v_lshlrev_b32_e32 v74, 16, v77
	v_and_b32_e32 v75, 0xffff0000, v77
	v_lshlrev_b32_e32 v76, 16, v78
	v_and_b32_e32 v77, 0xffff0000, v78
	v_lshlrev_b32_e32 v78, 16, v79
	v_and_b32_e32 v79, 0xffff0000, v79
	v_fmac_f32_e32 v67, 0x3f9837f0, v79
	v_fmamk_f32 v68, v72, 0x3f9837f0, v68
	v_fmamk_f32 v69, v73, 0x3f9837f0, v69
	v_fmamk_f32 v70, v74, 0x3f9837f0, v70
	v_fmac_f32_e32 v71, 0x3f9837f0, v75
	v_fmamk_f32 v72, v76, 0x3f9837f0, v64
	v_fmamk_f32 v73, v77, 0x3f9837f0, v65
	v_fmamk_f32 v74, v78, 0x3f9837f0, v66
	v_cvt_pk_bf16_f32 v64, v68, v69
	v_cvt_pk_bf16_f32 v65, v70, v71
	v_cvt_pk_bf16_f32 v66, v72, v73
	v_cvt_pk_bf16_f32 v67, v74, v67
	global_store_dwordx4 v[82:83], v[64:67], off offset:256
	s_waitcnt vmcnt(11)
	s_nop 1
	v_mov_b32_e32 v64, v234
	v_mov_b32_e32 v65, v235
	v_mov_b32_e32 v66, v236
	v_mov_b32_e32 v67, v237
	s_mov_b64 s[98:99], 0x58000
	v_lshl_add_u64 v[250:251], v[252:253], 0, s[98:99]
	global_load_dwordx4 v[234:237], v[250:251], off
	v_lshlrev_b32_e32 v68, 16, v64
	v_and_b32_e32 v64, 0xffff0000, v64
	v_lshlrev_b32_e32 v69, 16, v65
	v_and_b32_e32 v65, 0xffff0000, v65
	v_lshlrev_b32_e32 v71, 16, v67
	v_and_b32_e32 v67, 0xffff0000, v67
	v_lshlrev_b32_e32 v70, 16, v66
	v_and_b32_e32 v66, 0xffff0000, v66
	v_fmamk_f32 v60, v68, 0x3f9837f0, v60
	v_fmamk_f32 v61, v64, 0x3f9837f0, v61
	v_fmamk_f32 v62, v69, 0x3f9837f0, v62
	v_fmac_f32_e32 v63, 0x3f9837f0, v65
	v_fmac_f32_e32 v59, 0x3f9837f0, v67
	v_fmamk_f32 v64, v70, 0x3f9837f0, v56
	v_fmamk_f32 v65, v66, 0x3f9837f0, v57
	v_fmamk_f32 v66, v71, 0x3f9837f0, v58
	v_cvt_pk_bf16_f32 v56, v60, v61
	v_cvt_pk_bf16_f32 v57, v62, v63
	v_cvt_pk_bf16_f32 v58, v64, v65
	v_cvt_pk_bf16_f32 v59, v66, v59
	v_lshl_add_u64 v[66:67], s[12:13], 0, v[80:81]
	global_store_dwordx4 v[66:67], v[56:59], off
	v_lshl_add_u64 v[64:65], v[144:145], 0, s[22:23]
	v_lshl_add_u64 v[68:69], s[14:15], 0, v[64:65]
	s_waitcnt vmcnt(11)
	s_nop 1
	v_mov_b32_e32 v60, v238
	v_mov_b32_e32 v61, v239
	v_mov_b32_e32 v62, v240
	v_mov_b32_e32 v63, v241
	global_load_dwordx4 v[238:241], v[250:251], off offset:256
	v_lshlrev_b32_e32 v56, 16, v60
	v_and_b32_e32 v57, 0xffff0000, v60
	v_lshlrev_b32_e32 v58, 16, v61
	v_and_b32_e32 v59, 0xffff0000, v61
	v_lshlrev_b32_e32 v60, 16, v62
	v_and_b32_e32 v61, 0xffff0000, v62
	v_lshlrev_b32_e32 v62, 16, v63
	v_and_b32_e32 v63, 0xffff0000, v63
	v_fmac_f32_e32 v51, 0x3f9837f0, v63
	v_fmamk_f32 v52, v56, 0x3f9837f0, v52
	v_fmamk_f32 v53, v57, 0x3f9837f0, v53
	v_fmamk_f32 v54, v58, 0x3f9837f0, v54
	v_fmac_f32_e32 v55, 0x3f9837f0, v59
	v_fmamk_f32 v56, v60, 0x3f9837f0, v48
	v_fmamk_f32 v57, v61, 0x3f9837f0, v49
	v_fmamk_f32 v58, v62, 0x3f9837f0, v50
	v_cvt_pk_bf16_f32 v48, v52, v53
	v_cvt_pk_bf16_f32 v49, v54, v55
	v_cvt_pk_bf16_f32 v50, v56, v57
	v_cvt_pk_bf16_f32 v51, v58, v51
	global_store_dwordx4 v[66:67], v[48:51], off offset:256
	s_waitcnt vmcnt(11)
	s_nop 1
	v_mov_b32_e32 v48, v242
	v_mov_b32_e32 v49, v243
	v_mov_b32_e32 v50, v244
	v_mov_b32_e32 v51, v245
	v_lshlrev_b32_e32 v52, 16, v48
	v_and_b32_e32 v48, 0xffff0000, v48
	v_lshlrev_b32_e32 v53, 16, v49
	v_and_b32_e32 v49, 0xffff0000, v49
	v_lshlrev_b32_e32 v55, 16, v51
	v_and_b32_e32 v51, 0xffff0000, v51
	v_lshlrev_b32_e32 v54, 16, v50
	v_and_b32_e32 v50, 0xffff0000, v50
	v_fmamk_f32 v44, v52, 0x3f9837f0, v44
	v_fmamk_f32 v45, v48, 0x3f9837f0, v45
	v_fmamk_f32 v46, v53, 0x3f9837f0, v46
	v_fmac_f32_e32 v47, 0x3f9837f0, v49
	v_fmac_f32_e32 v43, 0x3f9837f0, v51
	v_fmamk_f32 v48, v54, 0x3f9837f0, v40
	v_fmamk_f32 v49, v50, 0x3f9837f0, v41
	v_fmamk_f32 v50, v55, 0x3f9837f0, v42
	v_cvt_pk_bf16_f32 v40, v44, v45
	v_cvt_pk_bf16_f32 v41, v46, v47
	v_cvt_pk_bf16_f32 v42, v48, v49
	v_cvt_pk_bf16_f32 v43, v50, v43
	v_lshl_add_u64 v[50:51], s[12:13], 0, v[64:65]
	global_store_dwordx4 v[50:51], v[40:43], off
	v_lshl_add_u64 v[48:49], v[144:145], 0, s[24:25]
	v_lshl_add_u64 v[52:53], s[14:15], 0, v[48:49]
	s_waitcnt vmcnt(10)
	s_nop 1
	v_mov_b32_e32 v44, v246
	v_mov_b32_e32 v45, v247
	v_mov_b32_e32 v46, v248
	v_mov_b32_e32 v47, v249
	v_lshlrev_b32_e32 v40, 16, v44
	v_and_b32_e32 v41, 0xffff0000, v44
	v_lshlrev_b32_e32 v42, 16, v45
	v_and_b32_e32 v43, 0xffff0000, v45
	v_lshlrev_b32_e32 v44, 16, v46
	v_and_b32_e32 v45, 0xffff0000, v46
	v_lshlrev_b32_e32 v46, 16, v47
	v_and_b32_e32 v47, 0xffff0000, v47
	v_fmac_f32_e32 v35, 0x3f9837f0, v47
	v_fmamk_f32 v36, v40, 0x3f9837f0, v36
	v_fmamk_f32 v37, v41, 0x3f9837f0, v37
	v_fmamk_f32 v38, v42, 0x3f9837f0, v38
	v_fmac_f32_e32 v39, 0x3f9837f0, v43
	v_fmamk_f32 v40, v44, 0x3f9837f0, v32
	v_fmamk_f32 v41, v45, 0x3f9837f0, v33
	v_fmamk_f32 v42, v46, 0x3f9837f0, v34
	v_cvt_pk_bf16_f32 v32, v36, v37
	v_cvt_pk_bf16_f32 v33, v38, v39
	v_cvt_pk_bf16_f32 v34, v40, v41
	v_cvt_pk_bf16_f32 v35, v42, v35
	global_store_dwordx4 v[50:51], v[32:35], off offset:256
	s_waitcnt vmcnt(9)
	s_nop 1
	v_mov_b32_e32 v32, v226
	v_mov_b32_e32 v33, v227
	v_mov_b32_e32 v34, v228
	v_mov_b32_e32 v35, v229
	v_lshlrev_b32_e32 v36, 16, v32
	v_and_b32_e32 v32, 0xffff0000, v32
	v_lshlrev_b32_e32 v37, 16, v33
	v_and_b32_e32 v33, 0xffff0000, v33
	v_lshlrev_b32_e32 v39, 16, v35
	v_and_b32_e32 v35, 0xffff0000, v35
	v_lshlrev_b32_e32 v38, 16, v34
	v_and_b32_e32 v34, 0xffff0000, v34
	v_fmamk_f32 v28, v36, 0x3f9837f0, v28
	v_fmamk_f32 v29, v32, 0x3f9837f0, v29
	v_fmamk_f32 v30, v37, 0x3f9837f0, v30
	v_fmac_f32_e32 v31, 0x3f9837f0, v33
	v_fmac_f32_e32 v27, 0x3f9837f0, v35
	v_fmamk_f32 v32, v38, 0x3f9837f0, v24
	v_fmamk_f32 v33, v34, 0x3f9837f0, v25
	v_fmamk_f32 v34, v39, 0x3f9837f0, v26
	v_cvt_pk_bf16_f32 v24, v28, v29
	v_cvt_pk_bf16_f32 v25, v30, v31
	v_cvt_pk_bf16_f32 v26, v32, v33
	v_cvt_pk_bf16_f32 v27, v34, v27
	v_lshl_add_u64 v[34:35], s[12:13], 0, v[48:49]
	global_store_dwordx4 v[34:35], v[24:27], off
	v_lshl_add_u64 v[32:33], v[144:145], 0, s[26:27]
	v_lshl_add_u64 v[36:37], s[14:15], 0, v[32:33]
	s_waitcnt vmcnt(8)
	s_nop 1
	v_mov_b32_e32 v28, v230
	v_mov_b32_e32 v29, v231
	v_mov_b32_e32 v30, v232
	v_mov_b32_e32 v31, v233
	v_lshlrev_b32_e32 v24, 16, v28
	v_and_b32_e32 v25, 0xffff0000, v28
	v_lshlrev_b32_e32 v26, 16, v29
	v_and_b32_e32 v27, 0xffff0000, v29
	v_lshlrev_b32_e32 v28, 16, v30
	v_and_b32_e32 v29, 0xffff0000, v30
	v_lshlrev_b32_e32 v30, 16, v31
	v_and_b32_e32 v31, 0xffff0000, v31
	v_fmac_f32_e32 v19, 0x3f9837f0, v31
	v_fmamk_f32 v20, v24, 0x3f9837f0, v20
	v_fmamk_f32 v21, v25, 0x3f9837f0, v21
	v_fmamk_f32 v22, v26, 0x3f9837f0, v22
	v_fmac_f32_e32 v23, 0x3f9837f0, v27
	v_fmamk_f32 v24, v28, 0x3f9837f0, v16
	v_fmamk_f32 v25, v29, 0x3f9837f0, v17
	v_fmamk_f32 v26, v30, 0x3f9837f0, v18
	v_cvt_pk_bf16_f32 v16, v20, v21
	v_cvt_pk_bf16_f32 v17, v22, v23
	v_cvt_pk_bf16_f32 v18, v24, v25
	v_cvt_pk_bf16_f32 v19, v26, v19
	global_store_dwordx4 v[34:35], v[16:19], off offset:256
	s_waitcnt vmcnt(7)
	s_nop 1
	v_mov_b32_e32 v16, v234
	v_mov_b32_e32 v17, v235
	v_mov_b32_e32 v18, v236
	v_mov_b32_e32 v19, v237
	v_lshlrev_b32_e32 v20, 16, v16
	v_and_b32_e32 v16, 0xffff0000, v16
	v_lshlrev_b32_e32 v21, 16, v17
	v_and_b32_e32 v17, 0xffff0000, v17
	v_lshlrev_b32_e32 v23, 16, v19
	v_and_b32_e32 v19, 0xffff0000, v19
	v_lshlrev_b32_e32 v22, 16, v18
	v_and_b32_e32 v18, 0xffff0000, v18
	v_fmamk_f32 v12, v20, 0x3f9837f0, v12
	v_fmamk_f32 v13, v16, 0x3f9837f0, v13
	v_fmamk_f32 v14, v21, 0x3f9837f0, v14
	v_fmac_f32_e32 v15, 0x3f9837f0, v17
	v_fmac_f32_e32 v11, 0x3f9837f0, v19
	v_fmamk_f32 v16, v22, 0x3f9837f0, v8
	v_fmamk_f32 v17, v18, 0x3f9837f0, v9
	v_fmamk_f32 v18, v23, 0x3f9837f0, v10
	v_cvt_pk_bf16_f32 v8, v12, v13
	v_cvt_pk_bf16_f32 v9, v14, v15
	v_cvt_pk_bf16_f32 v10, v16, v17
	v_cvt_pk_bf16_f32 v11, v18, v11
	v_lshl_add_u64 v[16:17], s[12:13], 0, v[32:33]
	global_store_dwordx4 v[16:17], v[8:11], off
	s_waitcnt vmcnt(6)
	s_nop 1
	v_mov_b32_e32 v12, v238
	v_mov_b32_e32 v13, v239
	v_mov_b32_e32 v14, v240
	v_mov_b32_e32 v15, v241
	s_nop 0
	v_lshlrev_b32_e32 v8, 16, v12
	v_and_b32_e32 v9, 0xffff0000, v12
	v_lshlrev_b32_e32 v10, 16, v13
	v_and_b32_e32 v11, 0xffff0000, v13
	v_lshlrev_b32_e32 v12, 16, v14
	v_and_b32_e32 v13, 0xffff0000, v14
	v_lshlrev_b32_e32 v14, 16, v15
	v_and_b32_e32 v15, 0xffff0000, v15
	v_fmac_f32_e32 v3, 0x3f9837f0, v15
	v_fmamk_f32 v4, v8, 0x3f9837f0, v4
	v_fmamk_f32 v5, v9, 0x3f9837f0, v5
	v_fmamk_f32 v6, v10, 0x3f9837f0, v6
	v_fmac_f32_e32 v7, 0x3f9837f0, v11
	v_fmamk_f32 v8, v12, 0x3f9837f0, v0
	v_fmamk_f32 v9, v13, 0x3f9837f0, v1
	v_fmamk_f32 v10, v14, 0x3f9837f0, v2
	v_cvt_pk_bf16_f32 v0, v4, v5
	v_cvt_pk_bf16_f32 v1, v6, v7
	v_cvt_pk_bf16_f32 v2, v8, v9
	v_cvt_pk_bf16_f32 v3, v10, v3
	global_store_dwordx4 v[16:17], v[0:3], off offset:256
	s_cbranch_vccnz .LBB0_1572
	s_andn2_b64 vcc, exec, s[10:11]
	s_cbranch_vccnz .LBB0_1571
	s_barrier
	s_branch .LBB0_1571

.LBB0_1603:
	ds_read_b128 v[0:3], v141
	ds_read_b128 v[4:7], v141 offset:1024
	ds_read_b128 v[8:11], v141 offset:2048
	ds_read_b128 v[12:15], v141 offset:3072
	ds_read_b128 v[16:19], v142
	ds_read_b128 v[20:23], v142 offset:1024
	ds_read_b128 v[24:27], v142 offset:2048
	ds_read_b128 v[28:31], v142 offset:3072
	s_add_u32 s46, s40, 0xb0080
	s_addc_u32 s47, s41, 0
	s_mov_b32 m0, s62
	v_lshl_add_u64 v[64:65], s[46:47], 0, v[134:135]
	ds_read_b128 v[32:35], v143
	ds_read_b128 v[36:39], v143 offset:1024
	ds_read_b128 v[40:43], v143 offset:2048
	ds_read_b128 v[44:47], v143 offset:3072
	ds_read_b128 v[48:51], v143 offset:4096
	ds_read_b128 v[52:55], v143 offset:5120
	ds_read_b128 v[56:59], v143 offset:6144
	ds_read_b128 v[60:63], v143 offset:7168
	global_load_lds_dwordx4 v[64:65], off
	v_lshl_add_u64 v[64:65], s[46:47], 0, v[130:131]
	s_mov_b32 m0, s63
	s_nop 0
	global_load_lds_dwordx4 v[64:65], off
	s_waitcnt vmcnt(8)
	s_waitcnt lgkmcnt(0)
	s_barrier
	s_setprio 1
	s_waitcnt lgkmcnt(0)
	v_mfma_f32_16x16x32_bf16 v[64:67], v[0:3], v[32:35], 0
	v_mfma_f32_16x16x32_bf16 v[68:71], v[8:11], v[32:35], 0
	v_mfma_f32_16x16x32_bf16 v[72:75], v[0:3], v[40:43], 0
	v_mfma_f32_16x16x32_bf16 v[76:79], v[8:11], v[40:43], 0
	v_mfma_f32_16x16x32_bf16 v[80:83], v[0:3], v[48:51], 0
	v_mfma_f32_16x16x32_bf16 v[84:87], v[8:11], v[48:51], 0
	v_mfma_f32_16x16x32_bf16 v[88:91], v[0:3], v[56:59], 0
	v_mfma_f32_16x16x32_bf16 v[92:95], v[8:11], v[56:59], 0
	v_mfma_f32_16x16x32_bf16 v[64:67], v[4:7], v[36:39], v[64:67]
	v_mfma_f32_16x16x32_bf16 v[68:71], v[12:15], v[36:39], v[68:71]
	v_mfma_f32_16x16x32_bf16 v[72:75], v[4:7], v[44:47], v[72:75]
	v_mfma_f32_16x16x32_bf16 v[76:79], v[12:15], v[44:47], v[76:79]
	v_mfma_f32_16x16x32_bf16 v[80:83], v[4:7], v[52:55], v[80:83]
	v_mfma_f32_16x16x32_bf16 v[84:87], v[12:15], v[52:55], v[84:87]
	v_mfma_f32_16x16x32_bf16 v[88:91], v[4:7], v[60:63], v[88:91]
	v_mfma_f32_16x16x32_bf16 v[92:95], v[12:15], v[60:63], v[92:95]
	s_setprio 0
	s_setprio 1
	v_mfma_f32_16x16x32_bf16 v[96:99], v[16:19], v[32:35], 0
	v_mfma_f32_16x16x32_bf16 v[32:35], v[24:27], v[32:35], 0
	v_mfma_f32_16x16x32_bf16 v[96:99], v[20:23], v[36:39], v[96:99]
	v_mfma_f32_16x16x32_bf16 v[32:35], v[28:31], v[36:39], v[32:35]
	v_mfma_f32_16x16x32_bf16 v[36:39], v[16:19], v[40:43], 0
	v_mfma_f32_16x16x32_bf16 v[40:43], v[24:27], v[40:43], 0
	v_mfma_f32_16x16x32_bf16 v[36:39], v[20:23], v[44:47], v[36:39]
	v_mfma_f32_16x16x32_bf16 v[40:43], v[28:31], v[44:47], v[40:43]
	v_mfma_f32_16x16x32_bf16 v[44:47], v[16:19], v[48:51], 0
	v_mfma_f32_16x16x32_bf16 v[48:51], v[24:27], v[48:51], 0
	v_mfma_f32_16x16x32_bf16 v[44:47], v[20:23], v[52:55], v[44:47]
	v_mfma_f32_16x16x32_bf16 v[48:51], v[28:31], v[52:55], v[48:51]
	v_mfma_f32_16x16x32_bf16 v[52:55], v[16:19], v[56:59], 0
	v_mfma_f32_16x16x32_bf16 v[56:59], v[24:27], v[56:59], 0
	v_mfma_f32_16x16x32_bf16 v[52:55], v[20:23], v[60:63], v[52:55]
	v_mfma_f32_16x16x32_bf16 v[56:59], v[28:31], v[60:63], v[56:59]
	s_setprio 0
	s_barrier
	v_lshl_add_u64 v[136:137], s[42:43], 0, v[132:133]
	s_mov_b32 m0, s64
	v_lshl_add_u64 v[144:145], v[136:137], 0, s[12:13]
	v_lshl_add_u64 v[196:197], s[42:43], 0, v[128:129]
	s_add_u32 s46, s42, 0xb0100
	ds_read_b128 v[60:63], v143 offset:16384
	ds_read_b128 v[100:103], v143 offset:17408
	ds_read_b128 v[104:107], v143 offset:18432
	ds_read_b128 v[108:111], v143 offset:19456
	ds_read_b128 v[112:115], v143 offset:20480
	ds_read_b128 v[116:119], v143 offset:21504
	ds_read_b128 v[120:123], v143 offset:22528
	ds_read_b128 v[124:127], v143 offset:23552
	global_load_lds_dwordx4 v[144:145], off
	v_lshl_add_u64 v[144:145], v[196:197], 0, s[12:13]
	s_mov_b32 m0, s65
	s_addc_u32 s47, s43, 0
	s_add_i32 s25, s57, s35
	global_load_lds_dwordx4 v[144:145], off
	v_lshl_add_u64 v[144:145], s[46:47], 0, v[132:133]
	s_mov_b32 m0, s25
	v_lshl_add_u64 v[210:211], s[40:41], 0, v[134:135]
	global_load_lds_dwordx4 v[144:145], off
	v_lshl_add_u64 v[144:145], s[46:47], 0, v[128:129]
	s_add_i32 s46, s25, 0x2000
	s_mov_b32 m0, s46
	v_lshl_add_u64 v[212:213], s[40:41], 0, v[130:131]
	global_load_lds_dwordx4 v[144:145], off
	v_lshl_add_u64 v[144:145], v[210:211], 0, s[12:13]
	s_mov_b32 m0, s31
	s_nop 0
	global_load_lds_dwordx4 v[144:145], off
	v_lshl_add_u64 v[144:145], v[212:213], 0, s[12:13]
	s_mov_b32 m0, s49
	s_nop 0
	global_load_lds_dwordx4 v[144:145], off
	s_nop 0
	s_waitcnt vmcnt(8)
	s_waitcnt lgkmcnt(0)
	s_barrier
	s_setprio 1
	s_waitcnt lgkmcnt(0)
	v_mfma_f32_16x16x32_bf16 v[144:147], v[0:3], v[60:63], 0
	v_mfma_f32_16x16x32_bf16 v[152:155], v[0:3], v[104:107], 0
	v_mfma_f32_16x16x32_bf16 v[160:163], v[0:3], v[112:115], 0
	v_mfma_f32_16x16x32_bf16 v[0:3], v[0:3], v[120:123], 0
	v_mfma_f32_16x16x32_bf16 v[144:147], v[4:7], v[100:103], v[144:147]
	v_mfma_f32_16x16x32_bf16 v[152:155], v[4:7], v[108:111], v[152:155]
	v_mfma_f32_16x16x32_bf16 v[160:163], v[4:7], v[116:119], v[160:163]
	v_mfma_f32_16x16x32_bf16 v[0:3], v[4:7], v[124:127], v[0:3]
	v_mfma_f32_16x16x32_bf16 v[4:7], v[8:11], v[120:123], 0
	v_mfma_f32_16x16x32_bf16 v[148:151], v[8:11], v[60:63], 0
	v_mfma_f32_16x16x32_bf16 v[156:159], v[8:11], v[104:107], 0
	v_mfma_f32_16x16x32_bf16 v[164:167], v[8:11], v[112:115], 0
	v_mfma_f32_16x16x32_bf16 v[4:7], v[12:15], v[124:127], v[4:7]
	v_mfma_f32_16x16x32_bf16 v[148:151], v[12:15], v[100:103], v[148:151]
	v_mfma_f32_16x16x32_bf16 v[156:159], v[12:15], v[108:111], v[156:159]
	v_mfma_f32_16x16x32_bf16 v[164:167], v[12:15], v[116:119], v[164:167]
	s_setprio 0
	s_setprio 1
	v_mfma_f32_16x16x32_bf16 v[8:11], v[16:19], v[60:63], 0
	v_mfma_f32_16x16x32_bf16 v[12:15], v[24:27], v[60:63], 0
	v_mfma_f32_16x16x32_bf16 v[8:11], v[20:23], v[100:103], v[8:11]
	v_mfma_f32_16x16x32_bf16 v[12:15], v[28:31], v[100:103], v[12:15]
	v_mfma_f32_16x16x32_bf16 v[60:63], v[16:19], v[104:107], 0
	v_mfma_f32_16x16x32_bf16 v[100:103], v[24:27], v[104:107], 0
	v_mfma_f32_16x16x32_bf16 v[104:107], v[16:19], v[112:115], 0
	v_mfma_f32_16x16x32_bf16 v[16:19], v[16:19], v[120:123], 0
	v_mfma_f32_16x16x32_bf16 v[60:63], v[20:23], v[108:111], v[60:63]
	v_mfma_f32_16x16x32_bf16 v[100:103], v[28:31], v[108:111], v[100:103]
	v_mfma_f32_16x16x32_bf16 v[104:107], v[20:23], v[116:119], v[104:107]
	v_mfma_f32_16x16x32_bf16 v[108:111], v[24:27], v[112:115], 0
	v_mfma_f32_16x16x32_bf16 v[16:19], v[20:23], v[124:127], v[16:19]
	v_mfma_f32_16x16x32_bf16 v[20:23], v[24:27], v[120:123], 0
	v_mfma_f32_16x16x32_bf16 v[108:111], v[28:31], v[116:119], v[108:111]
	v_mfma_f32_16x16x32_bf16 v[20:23], v[28:31], v[124:127], v[20:23]
	s_setprio 0
	s_barrier
	s_add_i32 s47, 0, 0x18000
	s_add_i32 s74, 0, 0x1c000
	v_add_u32_e32 v222, s47, v138
	v_add_u32_e32 v230, s74, v138
	ds_read_b128 v[24:27], v222
	ds_read_b128 v[28:31], v222 offset:1024
	ds_read_b128 v[112:115], v222 offset:2048
	ds_read_b128 v[116:119], v222 offset:3072
	ds_read_b128 v[120:123], v230
	ds_read_b128 v[124:127], v230 offset:1024
	ds_read_b128 v[168:171], v230 offset:2048
	ds_read_b128 v[172:175], v230 offset:3072
	s_add_u32 s70, s40, 0xb0100
	s_addc_u32 s71, s41, 0
	s_mov_b32 m0, s50
	v_lshl_add_u64 v[214:215], s[70:71], 0, v[134:135]
	ds_read_b128 v[176:179], v143 offset:32768
	ds_read_b128 v[180:183], v143 offset:33792
	ds_read_b128 v[184:187], v143 offset:34816
	ds_read_b128 v[188:191], v143 offset:35840
	ds_read_b128 v[192:195], v143 offset:36864
	ds_read_b128 v[198:201], v143 offset:37888
	ds_read_b128 v[202:205], v143 offset:38912
	ds_read_b128 v[206:209], v143 offset:39936
	global_load_lds_dwordx4 v[214:215], off
	v_lshl_add_u64 v[214:215], s[70:71], 0, v[130:131]
	s_mov_b32 m0, s51
	s_nop 0
	global_load_lds_dwordx4 v[214:215], off
	s_nop 0
	s_waitcnt vmcnt(8)
	s_waitcnt lgkmcnt(0)
	s_barrier
	s_setprio 1
	s_waitcnt lgkmcnt(0)
	v_mfma_f32_16x16x32_bf16 v[64:67], v[24:27], v[176:179], v[64:67]
	v_mfma_f32_16x16x32_bf16 v[68:71], v[112:115], v[176:179], v[68:71]
	v_mfma_f32_16x16x32_bf16 v[72:75], v[24:27], v[184:187], v[72:75]
	v_mfma_f32_16x16x32_bf16 v[76:79], v[112:115], v[184:187], v[76:79]
	v_mfma_f32_16x16x32_bf16 v[80:83], v[24:27], v[192:195], v[80:83]
	v_mfma_f32_16x16x32_bf16 v[84:87], v[112:115], v[192:195], v[84:87]
	v_mfma_f32_16x16x32_bf16 v[88:91], v[24:27], v[202:205], v[88:91]
	v_mfma_f32_16x16x32_bf16 v[92:95], v[112:115], v[202:205], v[92:95]
	v_mfma_f32_16x16x32_bf16 v[64:67], v[28:31], v[180:183], v[64:67]
	v_mfma_f32_16x16x32_bf16 v[68:71], v[116:119], v[180:183], v[68:71]
	v_mfma_f32_16x16x32_bf16 v[72:75], v[28:31], v[188:191], v[72:75]
	v_mfma_f32_16x16x32_bf16 v[76:79], v[116:119], v[188:191], v[76:79]
	v_mfma_f32_16x16x32_bf16 v[80:83], v[28:31], v[198:201], v[80:83]
	v_mfma_f32_16x16x32_bf16 v[84:87], v[116:119], v[198:201], v[84:87]
	v_mfma_f32_16x16x32_bf16 v[88:91], v[28:31], v[206:209], v[88:91]
	v_mfma_f32_16x16x32_bf16 v[92:95], v[116:119], v[206:209], v[92:95]
	s_setprio 0
	s_setprio 1
	v_mfma_f32_16x16x32_bf16 v[96:99], v[120:123], v[176:179], v[96:99]
	v_mfma_f32_16x16x32_bf16 v[32:35], v[168:171], v[176:179], v[32:35]
	v_mfma_f32_16x16x32_bf16 v[36:39], v[120:123], v[184:187], v[36:39]
	v_mfma_f32_16x16x32_bf16 v[40:43], v[168:171], v[184:187], v[40:43]
	v_mfma_f32_16x16x32_bf16 v[44:47], v[120:123], v[192:195], v[44:47]
	v_mfma_f32_16x16x32_bf16 v[48:51], v[168:171], v[192:195], v[48:51]
	v_mfma_f32_16x16x32_bf16 v[52:55], v[120:123], v[202:205], v[52:55]
	v_mfma_f32_16x16x32_bf16 v[56:59], v[168:171], v[202:205], v[56:59]
	v_mfma_f32_16x16x32_bf16 v[96:99], v[124:127], v[180:183], v[96:99]
	v_mfma_f32_16x16x32_bf16 v[32:35], v[172:175], v[180:183], v[32:35]
	v_mfma_f32_16x16x32_bf16 v[36:39], v[124:127], v[188:191], v[36:39]
	v_mfma_f32_16x16x32_bf16 v[40:43], v[172:175], v[188:191], v[40:43]
	v_mfma_f32_16x16x32_bf16 v[44:47], v[124:127], v[198:201], v[44:47]
	v_mfma_f32_16x16x32_bf16 v[48:51], v[172:175], v[198:201], v[48:51]
	v_mfma_f32_16x16x32_bf16 v[52:55], v[124:127], v[206:209], v[52:55]
	v_mfma_f32_16x16x32_bf16 v[56:59], v[172:175], v[206:209], v[56:59]
	s_setprio 0
	s_barrier
	s_add_i32 s70, s47, s35
	s_add_i32 s47, s70, 0x2000
	v_lshl_add_u64 v[136:137], v[136:137], 0, s[14:15]
	s_mov_b32 m0, s70
	s_add_u32 s72, s42, 0xb0180
	ds_read_b128 v[176:179], v143 offset:49152
	ds_read_b128 v[180:183], v143 offset:50176
	ds_read_b128 v[184:187], v143 offset:51200
	ds_read_b128 v[188:191], v143 offset:52224
	ds_read_b128 v[192:195], v143 offset:53248
	ds_read_b128 v[198:201], v143 offset:54272
	ds_read_b128 v[202:205], v143 offset:55296
	ds_read_b128 v[206:209], v143 offset:56320
	global_load_lds_dwordx4 v[136:137], off
	v_lshl_add_u64 v[136:137], v[196:197], 0, s[14:15]
	s_mov_b32 m0, s47
	s_addc_u32 s73, s43, 0
	s_add_i32 s42, s74, s35
	global_load_lds_dwordx4 v[136:137], off
	v_lshl_add_u64 v[136:137], s[72:73], 0, v[132:133]
	s_mov_b32 m0, s42
	s_add_i32 s43, s42, 0x2000
	global_load_lds_dwordx4 v[136:137], off
	v_lshl_add_u64 v[136:137], s[72:73], 0, v[128:129]
	s_mov_b32 m0, s43
	s_nop 0
	global_load_lds_dwordx4 v[136:137], off
	v_lshl_add_u64 v[136:137], v[210:211], 0, s[14:15]
	s_mov_b32 m0, s54
	s_nop 0
	global_load_lds_dwordx4 v[136:137], off
	v_lshl_add_u64 v[136:137], v[212:213], 0, s[14:15]
	s_mov_b32 m0, s55
	s_nop 0
	global_load_lds_dwordx4 v[136:137], off
	s_nop 0
	s_waitcnt vmcnt(8)
	s_waitcnt lgkmcnt(0)
	s_barrier
	s_setprio 1
	s_waitcnt lgkmcnt(0)
	v_mfma_f32_16x16x32_bf16 v[0:3], v[24:27], v[202:205], v[0:3]
	v_mfma_f32_16x16x32_bf16 v[4:7], v[112:115], v[202:205], v[4:7]
	v_mfma_f32_16x16x32_bf16 v[144:147], v[24:27], v[176:179], v[144:147]
	v_mfma_f32_16x16x32_bf16 v[148:151], v[112:115], v[176:179], v[148:151]
	v_mfma_f32_16x16x32_bf16 v[152:155], v[24:27], v[184:187], v[152:155]
	v_mfma_f32_16x16x32_bf16 v[156:159], v[112:115], v[184:187], v[156:159]
	v_mfma_f32_16x16x32_bf16 v[160:163], v[24:27], v[192:195], v[160:163]
	v_mfma_f32_16x16x32_bf16 v[164:167], v[112:115], v[192:195], v[164:167]
	v_mfma_f32_16x16x32_bf16 v[0:3], v[28:31], v[206:209], v[0:3]
	v_mfma_f32_16x16x32_bf16 v[4:7], v[116:119], v[206:209], v[4:7]
	v_mfma_f32_16x16x32_bf16 v[144:147], v[28:31], v[180:183], v[144:147]
	v_mfma_f32_16x16x32_bf16 v[148:151], v[116:119], v[180:183], v[148:151]
	v_mfma_f32_16x16x32_bf16 v[152:155], v[28:31], v[188:191], v[152:155]
	v_mfma_f32_16x16x32_bf16 v[156:159], v[116:119], v[188:191], v[156:159]
	v_mfma_f32_16x16x32_bf16 v[160:163], v[28:31], v[198:201], v[160:163]
	v_mfma_f32_16x16x32_bf16 v[164:167], v[116:119], v[198:201], v[164:167]
	s_setprio 0
	s_setprio 1
	v_mfma_f32_16x16x32_bf16 v[8:11], v[120:123], v[176:179], v[8:11]
	v_mfma_f32_16x16x32_bf16 v[12:15], v[168:171], v[176:179], v[12:15]
	v_mfma_f32_16x16x32_bf16 v[24:27], v[120:123], v[184:187], v[60:63]
	v_mfma_f32_16x16x32_bf16 v[28:31], v[168:171], v[184:187], v[100:103]
	v_mfma_f32_16x16x32_bf16 v[60:63], v[120:123], v[192:195], v[104:107]
	v_mfma_f32_16x16x32_bf16 v[100:103], v[168:171], v[192:195], v[108:111]
	v_mfma_f32_16x16x32_bf16 v[16:19], v[120:123], v[202:205], v[16:19]
	v_mfma_f32_16x16x32_bf16 v[20:23], v[168:171], v[202:205], v[20:23]
	v_mfma_f32_16x16x32_bf16 v[8:11], v[124:127], v[180:183], v[8:11]
	v_mfma_f32_16x16x32_bf16 v[12:15], v[172:175], v[180:183], v[12:15]
	v_mfma_f32_16x16x32_bf16 v[24:27], v[124:127], v[188:191], v[24:27]
	v_mfma_f32_16x16x32_bf16 v[28:31], v[172:175], v[188:191], v[28:31]
	v_mfma_f32_16x16x32_bf16 v[60:63], v[124:127], v[198:201], v[60:63]
	v_mfma_f32_16x16x32_bf16 v[100:103], v[172:175], v[198:201], v[100:103]
	v_mfma_f32_16x16x32_bf16 v[16:19], v[124:127], v[206:209], v[16:19]
	v_mfma_f32_16x16x32_bf16 v[20:23], v[172:175], v[206:209], v[20:23]
	s_setprio 0
	s_barrier
	ds_read_b128 v[104:107], v141
	ds_read_b128 v[108:111], v141 offset:1024
	ds_read_b128 v[112:115], v141 offset:2048
	ds_read_b128 v[116:119], v141 offset:3072
	ds_read_b128 v[120:123], v142
	ds_read_b128 v[124:127], v142 offset:1024
	ds_read_b128 v[168:171], v142 offset:2048
	ds_read_b128 v[172:175], v142 offset:3072
	s_add_u32 s40, s40, 0xb0180
	s_addc_u32 s41, s41, 0
	s_mov_b32 m0, s62
	v_lshl_add_u64 v[136:137], s[40:41], 0, v[134:135]
	ds_read_b128 v[176:179], v143
	ds_read_b128 v[180:183], v143 offset:1024
	ds_read_b128 v[184:187], v143 offset:2048
	ds_read_b128 v[188:191], v143 offset:3072
	ds_read_b128 v[192:195], v143 offset:4096
	ds_read_b128 v[198:201], v143 offset:5120
	ds_read_b128 v[202:205], v143 offset:6144
	ds_read_b128 v[206:209], v143 offset:7168
	global_load_lds_dwordx4 v[136:137], off
	v_lshl_add_u64 v[136:137], s[40:41], 0, v[130:131]
	s_mov_b32 m0, s63
	s_nop 0
	global_load_lds_dwordx4 v[136:137], off
	s_nop 0
	s_waitcnt vmcnt(8)
	s_waitcnt lgkmcnt(0)
	s_barrier
	s_setprio 1
	s_waitcnt lgkmcnt(0)
	v_mfma_f32_16x16x32_bf16 v[88:91], v[104:107], v[202:205], v[88:91]
	v_mfma_f32_16x16x32_bf16 v[64:67], v[104:107], v[176:179], v[64:67]
	v_mfma_f32_16x16x32_bf16 v[68:71], v[112:115], v[176:179], v[68:71]
	v_mfma_f32_16x16x32_bf16 v[72:75], v[104:107], v[184:187], v[72:75]
	v_mfma_f32_16x16x32_bf16 v[76:79], v[112:115], v[184:187], v[76:79]
	v_mfma_f32_16x16x32_bf16 v[80:83], v[104:107], v[192:195], v[80:83]
	v_mfma_f32_16x16x32_bf16 v[84:87], v[112:115], v[192:195], v[84:87]
	v_mfma_f32_16x16x32_bf16 v[210:213], v[108:111], v[206:209], v[88:91]
	v_mfma_f32_16x16x32_bf16 v[88:91], v[112:115], v[202:205], v[92:95]
	v_mfma_f32_16x16x32_bf16 v[64:67], v[108:111], v[180:183], v[64:67]
	v_mfma_f32_16x16x32_bf16 v[68:71], v[116:119], v[180:183], v[68:71]
	v_mfma_f32_16x16x32_bf16 v[72:75], v[108:111], v[188:191], v[72:75]
	v_mfma_f32_16x16x32_bf16 v[76:79], v[116:119], v[188:191], v[76:79]
	v_mfma_f32_16x16x32_bf16 v[80:83], v[108:111], v[198:201], v[80:83]
	v_mfma_f32_16x16x32_bf16 v[84:87], v[116:119], v[198:201], v[84:87]
	v_mfma_f32_16x16x32_bf16 v[92:95], v[116:119], v[206:209], v[88:91]
	s_setprio 0
	s_setprio 1
	v_mfma_f32_16x16x32_bf16 v[48:51], v[168:171], v[192:195], v[48:51]
	v_mfma_f32_16x16x32_bf16 v[88:91], v[120:123], v[176:179], v[96:99]
	v_mfma_f32_16x16x32_bf16 v[32:35], v[168:171], v[176:179], v[32:35]
	v_mfma_f32_16x16x32_bf16 v[36:39], v[120:123], v[184:187], v[36:39]
	v_mfma_f32_16x16x32_bf16 v[40:43], v[168:171], v[184:187], v[40:43]
	v_mfma_f32_16x16x32_bf16 v[44:47], v[120:123], v[192:195], v[44:47]
	v_mfma_f32_16x16x32_bf16 v[176:179], v[172:175], v[198:201], v[48:51]
	v_mfma_f32_16x16x32_bf16 v[48:51], v[120:123], v[202:205], v[52:55]
	v_mfma_f32_16x16x32_bf16 v[32:35], v[172:175], v[180:183], v[32:35]
	v_mfma_f32_16x16x32_bf16 v[36:39], v[124:127], v[188:191], v[36:39]
	v_mfma_f32_16x16x32_bf16 v[40:43], v[172:175], v[188:191], v[40:43]
	v_mfma_f32_16x16x32_bf16 v[44:47], v[124:127], v[198:201], v[44:47]
	v_mfma_f32_16x16x32_bf16 v[52:55], v[124:127], v[206:209], v[48:51]
	v_mfma_f32_16x16x32_bf16 v[48:51], v[168:171], v[202:205], v[56:59]
	v_mfma_f32_16x16x32_bf16 v[214:217], v[124:127], v[180:183], v[88:91]
	v_mfma_f32_16x16x32_bf16 v[180:183], v[172:175], v[206:209], v[48:51]
	s_setprio 0
	s_barrier
	s_mov_b32 m0, s64
	v_lshl_add_u64 v[136:137], s[28:29], 0, v[132:133]
	s_add_u32 s40, s28, 0xb0000
	s_nop 0
	ds_read_b128 v[48:51], v143 offset:16384
	ds_read_b128 v[56:59], v143 offset:17408
	ds_read_b128 v[88:91], v143 offset:18432
	ds_read_b128 v[96:99], v143 offset:19456
	ds_read_b128 v[184:187], v143 offset:20480
	ds_read_b128 v[188:191], v143 offset:21504
	ds_read_b128 v[192:195], v143 offset:22528
	ds_read_b128 v[198:201], v143 offset:23552
	global_load_lds_dwordx4 v[136:137], off
	v_lshl_add_u64 v[196:197], s[28:29], 0, v[128:129]
	s_mov_b32 m0, s65
	s_addc_u32 s41, s29, 0
	global_load_lds_dwordx4 v[196:197], off
	v_lshl_add_u64 v[202:203], s[40:41], 0, v[132:133]
	s_mov_b32 m0, s25
	v_lshl_add_u64 v[250:251], s[26:27], 0, v[134:135]
	global_load_lds_dwordx4 v[202:203], off
	v_lshl_add_u64 v[202:203], s[40:41], 0, v[128:129]
	s_mov_b32 m0, s46
	v_lshl_add_u64 v[252:253], s[26:27], 0, v[130:131]
	global_load_lds_dwordx4 v[202:203], off
	s_mov_b32 m0, s31
	s_nop 0
	global_load_lds_dwordx4 v[250:251], off
	s_mov_b32 m0, s49
	s_nop 0
	global_load_lds_dwordx4 v[252:253], off
	s_nop 0
	s_waitcnt vmcnt(8)
	s_waitcnt lgkmcnt(0)
	s_barrier
	s_setprio 1
	s_waitcnt lgkmcnt(0)
	v_mfma_f32_16x16x32_bf16 v[0:3], v[104:107], v[192:195], v[0:3]
	v_mfma_f32_16x16x32_bf16 v[4:7], v[112:115], v[192:195], v[4:7]
	v_mfma_f32_16x16x32_bf16 v[144:147], v[104:107], v[48:51], v[144:147]
	v_mfma_f32_16x16x32_bf16 v[148:151], v[112:115], v[48:51], v[148:151]
	v_mfma_f32_16x16x32_bf16 v[152:155], v[104:107], v[88:91], v[152:155]
	v_mfma_f32_16x16x32_bf16 v[156:159], v[112:115], v[88:91], v[156:159]
	v_mfma_f32_16x16x32_bf16 v[160:163], v[104:107], v[184:187], v[160:163]
	v_mfma_f32_16x16x32_bf16 v[164:167], v[112:115], v[184:187], v[164:167]
	v_mfma_f32_16x16x32_bf16 v[0:3], v[108:111], v[198:201], v[0:3]
	v_mfma_f32_16x16x32_bf16 v[4:7], v[116:119], v[198:201], v[4:7]
	v_mfma_f32_16x16x32_bf16 v[144:147], v[108:111], v[56:59], v[144:147]
	v_mfma_f32_16x16x32_bf16 v[148:151], v[116:119], v[56:59], v[148:151]
	v_mfma_f32_16x16x32_bf16 v[152:155], v[108:111], v[96:99], v[152:155]
	v_mfma_f32_16x16x32_bf16 v[156:159], v[116:119], v[96:99], v[156:159]
	v_mfma_f32_16x16x32_bf16 v[160:163], v[108:111], v[188:191], v[160:163]
	v_mfma_f32_16x16x32_bf16 v[164:167], v[116:119], v[188:191], v[164:167]
	s_setprio 0
	s_setprio 1
	v_mfma_f32_16x16x32_bf16 v[12:15], v[168:171], v[48:51], v[12:15]
	v_mfma_f32_16x16x32_bf16 v[202:205], v[172:175], v[56:59], v[12:15]
	v_mfma_f32_16x16x32_bf16 v[12:15], v[120:123], v[88:91], v[24:27]
	v_mfma_f32_16x16x32_bf16 v[24:27], v[124:127], v[96:99], v[12:15]
	v_mfma_f32_16x16x32_bf16 v[12:15], v[168:171], v[88:91], v[28:31]
	v_mfma_f32_16x16x32_bf16 v[206:209], v[172:175], v[96:99], v[12:15]
	v_mfma_f32_16x16x32_bf16 v[12:15], v[120:123], v[184:187], v[60:63]
	v_mfma_f32_16x16x32_bf16 v[218:221], v[124:127], v[188:191], v[12:15]
	v_mfma_f32_16x16x32_bf16 v[12:15], v[168:171], v[184:187], v[100:103]
	v_mfma_f32_16x16x32_bf16 v[8:11], v[120:123], v[48:51], v[8:11]
	v_mfma_f32_16x16x32_bf16 v[184:187], v[172:175], v[188:191], v[12:15]
	v_mfma_f32_16x16x32_bf16 v[12:15], v[120:123], v[192:195], v[16:19]
	v_mfma_f32_16x16x32_bf16 v[8:11], v[124:127], v[56:59], v[8:11]
	v_mfma_f32_16x16x32_bf16 v[188:191], v[124:127], v[198:201], v[12:15]
	v_mfma_f32_16x16x32_bf16 v[12:15], v[168:171], v[192:195], v[20:23]
	v_mfma_f32_16x16x32_bf16 v[168:171], v[172:175], v[198:201], v[12:15]
	s_setprio 0
	s_barrier
	s_nop 4
	ds_read_b128 v[12:15], v222
	ds_read_b128 v[16:19], v222 offset:1024
	ds_read_b128 v[172:175], v222 offset:2048
	ds_read_b128 v[192:195], v222 offset:3072
	ds_read_b128 v[198:201], v230
	ds_read_b128 v[222:225], v230 offset:1024
	ds_read_b128 v[226:229], v230 offset:2048
	ds_read_b128 v[230:233], v230 offset:3072
	s_add_u32 s40, s26, 0xb0000
	s_addc_u32 s41, s27, 0
	s_mov_b32 m0, s50
	v_lshl_add_u64 v[48:49], s[40:41], 0, v[134:135]
	ds_read_b128 v[20:23], v143 offset:32768
	ds_read_b128 v[28:31], v143 offset:33792
	ds_read_b128 v[60:63], v143 offset:34816
	ds_read_b128 v[100:103], v143 offset:35840
	ds_read_b128 v[234:237], v143 offset:36864
	ds_read_b128 v[238:241], v143 offset:37888
	ds_read_b128 v[242:245], v143 offset:38912
	ds_read_b128 v[246:249], v143 offset:39936
	global_load_lds_dwordx4 v[48:49], off
	v_lshl_add_u64 v[48:49], s[40:41], 0, v[130:131]
	s_mov_b32 m0, s51
	s_nop 0
	global_load_lds_dwordx4 v[48:49], off
	s_waitcnt vmcnt(8)
	s_waitcnt lgkmcnt(0)
	s_barrier
	s_setprio 1
	s_waitcnt lgkmcnt(0)
	v_mfma_f32_16x16x32_bf16 v[48:51], v[12:15], v[20:23], v[64:67]
	v_mfma_f32_16x16x32_bf16 v[120:123], v[16:19], v[28:31], v[48:51]
	v_mfma_f32_16x16x32_bf16 v[48:51], v[172:175], v[20:23], v[68:71]
	v_mfma_f32_16x16x32_bf16 v[112:115], v[192:195], v[28:31], v[48:51]
	v_mfma_f32_16x16x32_bf16 v[48:51], v[12:15], v[60:63], v[72:75]
	v_mfma_f32_16x16x32_bf16 v[104:107], v[16:19], v[100:103], v[48:51]
	v_mfma_f32_16x16x32_bf16 v[48:51], v[172:175], v[60:63], v[76:79]
	v_mfma_f32_16x16x32_bf16 v[96:99], v[192:195], v[100:103], v[48:51]
	v_mfma_f32_16x16x32_bf16 v[48:51], v[12:15], v[234:237], v[80:83]
	v_mfma_f32_16x16x32_bf16 v[88:91], v[16:19], v[238:241], v[48:51]
	v_mfma_f32_16x16x32_bf16 v[48:51], v[172:175], v[234:237], v[84:87]
	v_mfma_f32_16x16x32_bf16 v[80:83], v[192:195], v[238:241], v[48:51]
	v_mfma_f32_16x16x32_bf16 v[48:51], v[12:15], v[242:245], v[210:213]
	v_mfma_f32_16x16x32_bf16 v[56:59], v[16:19], v[246:249], v[48:51]
	v_mfma_f32_16x16x32_bf16 v[48:51], v[172:175], v[242:245], v[92:95]
	v_mfma_f32_16x16x32_bf16 v[48:51], v[192:195], v[246:249], v[48:51]
	s_setprio 0
	s_setprio 1
	v_mfma_f32_16x16x32_bf16 v[64:67], v[198:201], v[20:23], v[214:217]
	v_mfma_f32_16x16x32_bf16 v[20:23], v[226:229], v[20:23], v[32:35]
	v_mfma_f32_16x16x32_bf16 v[116:119], v[230:233], v[28:31], v[20:23]
	v_mfma_f32_16x16x32_bf16 v[20:23], v[198:201], v[60:63], v[36:39]
	v_mfma_f32_16x16x32_bf16 v[108:111], v[222:225], v[100:103], v[20:23]
	v_mfma_f32_16x16x32_bf16 v[20:23], v[226:229], v[60:63], v[40:43]
	v_mfma_f32_16x16x32_bf16 v[100:103], v[230:233], v[100:103], v[20:23]
	v_mfma_f32_16x16x32_bf16 v[20:23], v[198:201], v[234:237], v[44:47]
	v_mfma_f32_16x16x32_bf16 v[92:95], v[222:225], v[238:241], v[20:23]
	v_mfma_f32_16x16x32_bf16 v[20:23], v[226:229], v[234:237], v[176:179]
	v_mfma_f32_16x16x32_bf16 v[84:87], v[230:233], v[238:241], v[20:23]
	v_mfma_f32_16x16x32_bf16 v[20:23], v[198:201], v[242:245], v[52:55]
	v_mfma_f32_16x16x32_bf16 v[60:63], v[222:225], v[246:249], v[20:23]
	v_mfma_f32_16x16x32_bf16 v[20:23], v[226:229], v[242:245], v[180:183]
	v_mfma_f32_16x16x32_bf16 v[124:127], v[222:225], v[28:31], v[64:67]
	v_mfma_f32_16x16x32_bf16 v[52:55], v[230:233], v[246:249], v[20:23]
	s_setprio 0
	s_barrier
	s_mov_b32 m0, s70
	s_nop 2
	v_lshl_add_u64 v[20:21], v[136:137], 0, s[8:9]
	s_add_u32 s40, s28, 0xb0080
	ds_read_b128 v[32:35], v143 offset:49152
	ds_read_b128 v[40:43], v143 offset:50176
	ds_read_b128 v[176:179], v143 offset:51200
	ds_read_b128 v[180:183], v143 offset:52224
	ds_read_b128 v[210:213], v143 offset:53248
	ds_read_b128 v[214:217], v143 offset:54272
	ds_read_b128 v[234:237], v143 offset:55296
	ds_read_b128 v[238:241], v143 offset:56320
	global_load_lds_dwordx4 v[20:21], off
	v_lshl_add_u64 v[20:21], v[196:197], 0, s[8:9]
	s_mov_b32 m0, s47
	s_addc_u32 s41, s29, 0
	global_load_lds_dwordx4 v[20:21], off
	v_lshl_add_u64 v[20:21], s[40:41], 0, v[132:133]
	s_mov_b32 m0, s42
	s_nop 0
	global_load_lds_dwordx4 v[20:21], off
	v_lshl_add_u64 v[20:21], s[40:41], 0, v[128:129]
	s_mov_b32 m0, s43
	s_nop 0
	global_load_lds_dwordx4 v[20:21], off
	v_lshl_add_u64 v[20:21], v[250:251], 0, s[8:9]
	s_mov_b32 m0, s54
	s_nop 0
	global_load_lds_dwordx4 v[20:21], off
	v_lshl_add_u64 v[20:21], v[252:253], 0, s[8:9]
	s_mov_b32 m0, s55
	s_nop 0
	global_load_lds_dwordx4 v[20:21], off
	s_nop 0
	s_waitcnt vmcnt(8)
	s_waitcnt lgkmcnt(0)
	s_barrier
	s_setprio 1
	s_waitcnt lgkmcnt(0)
	v_mfma_f32_16x16x32_bf16 v[20:23], v[12:15], v[32:35], v[144:147]
	v_mfma_f32_16x16x32_bf16 v[76:79], v[16:19], v[40:43], v[20:23]
	v_mfma_f32_16x16x32_bf16 v[20:23], v[172:175], v[32:35], v[148:151]
	v_mfma_f32_16x16x32_bf16 v[68:71], v[192:195], v[40:43], v[20:23]
	v_mfma_f32_16x16x32_bf16 v[20:23], v[12:15], v[176:179], v[152:155]
	v_mfma_f32_16x16x32_bf16 v[44:47], v[16:19], v[180:183], v[20:23]
	v_mfma_f32_16x16x32_bf16 v[20:23], v[172:175], v[176:179], v[156:159]
	v_mfma_f32_16x16x32_bf16 v[36:39], v[192:195], v[180:183], v[20:23]
	v_mfma_f32_16x16x32_bf16 v[20:23], v[12:15], v[210:213], v[160:163]
	v_mfma_f32_16x16x32_bf16 v[0:3], v[12:15], v[234:237], v[0:3]
	v_mfma_f32_16x16x32_bf16 v[28:31], v[16:19], v[214:217], v[20:23]
	v_mfma_f32_16x16x32_bf16 v[20:23], v[172:175], v[210:213], v[164:167]
	v_mfma_f32_16x16x32_bf16 v[12:15], v[16:19], v[238:241], v[0:3]
	v_mfma_f32_16x16x32_bf16 v[0:3], v[172:175], v[234:237], v[4:7]
	v_mfma_f32_16x16x32_bf16 v[20:23], v[192:195], v[214:217], v[20:23]
	v_mfma_f32_16x16x32_bf16 v[4:7], v[192:195], v[238:241], v[0:3]
	s_setprio 0
	s_setprio 1
	v_mfma_f32_16x16x32_bf16 v[0:3], v[198:201], v[32:35], v[8:11]
	v_mfma_f32_16x16x32_bf16 v[72:75], v[222:225], v[40:43], v[0:3]
	v_mfma_f32_16x16x32_bf16 v[0:3], v[226:229], v[32:35], v[202:205]
	v_mfma_f32_16x16x32_bf16 v[64:67], v[230:233], v[40:43], v[0:3]
	v_mfma_f32_16x16x32_bf16 v[0:3], v[198:201], v[176:179], v[24:27]
	v_mfma_f32_16x16x32_bf16 v[40:43], v[222:225], v[180:183], v[0:3]
	v_mfma_f32_16x16x32_bf16 v[0:3], v[226:229], v[176:179], v[206:209]
	v_mfma_f32_16x16x32_bf16 v[32:35], v[230:233], v[180:183], v[0:3]
	v_mfma_f32_16x16x32_bf16 v[0:3], v[198:201], v[210:213], v[218:221]
	v_mfma_f32_16x16x32_bf16 v[24:27], v[222:225], v[214:217], v[0:3]
	v_mfma_f32_16x16x32_bf16 v[0:3], v[226:229], v[210:213], v[184:187]
	v_mfma_f32_16x16x32_bf16 v[16:19], v[230:233], v[214:217], v[0:3]
	v_mfma_f32_16x16x32_bf16 v[0:3], v[198:201], v[234:237], v[188:191]
	v_mfma_f32_16x16x32_bf16 v[8:11], v[222:225], v[238:241], v[0:3]
	v_mfma_f32_16x16x32_bf16 v[0:3], v[226:229], v[234:237], v[168:171]
	v_mfma_f32_16x16x32_bf16 v[0:3], v[230:233], v[238:241], v[0:3]
	s_setprio 0
	s_barrier
	s_andn2_b64 vcc, exec, s[10:11]
	s_cbranch_vccnz .LBB0_1605
	s_barrier
